# adds EpiGlu bias loads hoisted (12 drains removed), conversion-loop wait moved after processing, FINISH tail hoist and staging de-serialization in the sample GLA chunk
# speedup vs baseline: 1.0102x; 1.0102x over previous
.LBB0_87:
	s_waitcnt vmcnt(4)
	v_mov_b64_e32 v[2:3], v[34:35]
	v_mov_b64_e32 v[4:5], v[36:37]
	v_mov_b64_e32 v[6:7], v[38:39]
	v_mov_b64_e32 v[8:9], v[40:41]
	v_mov_b64_e32 v[10:11], v[42:43]
	v_mov_b64_e32 v[12:13], v[44:45]
	v_mov_b64_e32 v[14:15], v[46:47]
	v_mov_b64_e32 v[16:17], v[48:49]
	v_mov_b64_e32 v[18:19], v[50:51]
	v_mov_b64_e32 v[20:21], v[52:53]
	v_mov_b64_e32 v[22:23], v[54:55]
	v_mov_b64_e32 v[24:25], v[56:57]
	v_mov_b64_e32 v[26:27], v[58:59]
	v_mov_b64_e32 v[28:29], v[60:61]
	v_mov_b64_e32 v[30:31], v[62:63]
	v_mov_b64_e32 v[32:33], v[64:65]
	s_add_i32 s42, s42, s45
	v_mov_b32_e32 v65, v70
	v_mov_b32_e32 v64, v71
	v_mov_b32_e32 v63, v103
	v_mov_b32_e32 v62, v104
	v_mov_b32_e32 v61, v105
	v_mov_b32_e32 v60, v106
	v_mov_b32_e32 v59, v107
	v_mov_b32_e32 v58, v108
	v_mov_b32_e32 v57, v95
	v_mov_b32_e32 v56, v96
	v_mov_b32_e32 v55, v97
	v_mov_b32_e32 v54, v98
	v_mov_b32_e32 v53, v99
	v_mov_b32_e32 v52, v100
	v_mov_b32_e32 v51, v101
	v_mov_b32_e32 v50, v102
	v_mov_b32_e32 v49, v87
	v_mov_b32_e32 v48, v88
	v_mov_b32_e32 v47, v89
	v_mov_b32_e32 v46, v90
	v_mov_b32_e32 v45, v91
	v_mov_b32_e32 v44, v92
	v_mov_b32_e32 v43, v93
	v_mov_b32_e32 v42, v94
	v_mov_b32_e32 v41, v79
	v_mov_b32_e32 v40, v80
	v_mov_b32_e32 v39, v81
	v_mov_b32_e32 v38, v82
	v_mov_b32_e32 v37, v83
	v_mov_b32_e32 v36, v84
	v_mov_b32_e32 v35, v85
	v_mov_b32_e32 v34, v86
	s_mov_b32 s46, s49
	s_mov_b32 s43, s47
	s_mov_b32 s22, s48
	s_mov_b64 s[20:21], s[26:27]
	s_mov_b32 s49, s41
	s_mov_b32 s47, s61
	s_mov_b32 s48, s40
	s_mov_b64 s[26:27], s[30:31]
	s_andn2_b64 vcc, exec, s[34:35]
	s_mov_b64 s[24:25], s[28:29]
	s_cbranch_vccz .LBB0_120

.LBB0_116:
	v_cvt_f32_u32_e32 v69, s63
	s_sub_i32 s41, 0, s63
	s_abs_i32 s40, s62
	s_ashr_i32 s23, s62, 31
	v_rcp_iflag_f32_e32 v69, v69
	s_nop 0
	v_mul_f32_e32 v69, 0x4f7ffffe, v69
	v_cvt_u32_f32_e32 v69, v69
	s_nop 0
	v_readfirstlane_b32 s64, v69
	s_mul_i32 s41, s41, s64
	s_mul_hi_u32 s41, s64, s41
	s_add_i32 s64, s64, s41
	s_mul_hi_u32 s41, s40, s64
	s_mul_i32 s64, s41, s63
	s_sub_i32 s40, s40, s64
	s_add_i32 s65, s41, 1
	s_sub_i32 s64, s40, s63
	s_cmp_ge_u32 s40, s63
	s_cselect_b32 s41, s65, s41
	s_cselect_b32 s40, s64, s40
	s_add_i32 s64, s41, 1
	s_cmp_ge_u32 s40, s63
	s_cselect_b32 s40, s64, s41
	s_xor_b32 s40, s40, s23
	s_sub_i32 s23, s40, s23
	s_mul_i32 s40, s23, s63
	s_sub_i32 s62, s62, s40
	s_cmpk_gt_i32 s62, 0x7f
	s_cselect_b64 s[40:41], -1, 0
	s_and_b64 s[34:35], s[34:35], s[40:41]
	s_and_b64 s[34:35], s[34:35], exec
	s_cselect_b32 s34, 16, 0
	s_lshl_b32 s41, s62, 5
	s_or_b32 s34, s34, s41
	s_ashr_i32 s35, s34, 31
	s_lshl_b32 s40, s23, 6
	s_lshl_b64 s[34:35], s[34:35], 2
	s_add_u32 s34, s38, s34
	v_or_b32_e32 v69, s40, v1
	s_addc_u32 s35, s39, s35
	s_ashr_i32 s23, s40, 31
	v_lshl_add_u64 v[70:71], s[34:35], 0, v[66:67]
	s_mul_i32 s23, s36, s23
	v_mul_lo_u32 v79, s37, v69
	v_mad_u64_u32 v[80:81], s[34:35], s36, v69, 0
	v_add3_u32 v81, v81, s23, v79
	v_or_b32_e32 v79, 2, v69
	v_mul_lo_u32 v84, s37, v79
	v_mad_u64_u32 v[82:83], s[34:35], s36, v79, 0
	v_or_b32_e32 v79, 4, v69
	v_add3_u32 v83, v83, s23, v84
	v_mul_lo_u32 v86, s37, v79
	v_mad_u64_u32 v[84:85], s[34:35], s36, v79, 0
	v_add3_u32 v85, v85, s23, v86
	v_or_b32_e32 v79, 6, v69
	v_lshl_add_u64 v[88:89], v[84:85], 2, v[70:71]
	v_mul_lo_u32 v86, s37, v79
	v_mad_u64_u32 v[84:85], s[34:35], s36, v79, 0
	v_add3_u32 v85, v85, s23, v86
	v_or_b32_e32 v79, 8, v69
	v_lshl_add_u64 v[90:91], v[84:85], 2, v[70:71]
	v_mul_lo_u32 v86, s37, v79
	v_mad_u64_u32 v[84:85], s[34:35], s36, v79, 0
	v_add3_u32 v85, v85, s23, v86
	v_or_b32_e32 v79, 10, v69
	v_lshl_add_u64 v[92:93], v[84:85], 2, v[70:71]
	v_mul_lo_u32 v86, s37, v79
	v_mad_u64_u32 v[84:85], s[34:35], s36, v79, 0
	v_add3_u32 v85, v85, s23, v86
	v_or_b32_e32 v79, 12, v69
	v_lshl_add_u64 v[94:95], v[84:85], 2, v[70:71]
	v_mul_lo_u32 v86, s37, v79
	v_mad_u64_u32 v[84:85], s[34:35], s36, v79, 0
	v_add3_u32 v85, v85, s23, v86
	v_or_b32_e32 v79, 14, v69
	v_lshl_add_u64 v[96:97], v[84:85], 2, v[70:71]
	v_mul_lo_u32 v86, s37, v79
	v_mad_u64_u32 v[84:85], s[34:35], s36, v79, 0
	v_lshl_add_u64 v[80:81], v[80:81], 2, v[70:71]
	v_lshl_add_u64 v[82:83], v[82:83], 2, v[70:71]
	v_add3_u32 v85, v85, s23, v86
	v_or_b32_e32 v87, 16, v69
	v_lshl_add_u64 v[98:99], v[84:85], 2, v[70:71]
	global_load_dword v86, v[80:81], off
	global_load_dword v85, v[82:83], off
	global_load_dword v84, v[88:89], off
	s_nop 0
	global_load_dword v83, v[90:91], off
	global_load_dword v82, v[92:93], off
	global_load_dword v81, v[94:95], off
	global_load_dword v80, v[96:97], off
	global_load_dword v79, v[98:99], off
	v_mul_lo_u32 v90, s37, v87
	v_mad_u64_u32 v[88:89], s[34:35], s36, v87, 0
	v_or_b32_e32 v87, 18, v69
	v_add3_u32 v89, v89, s23, v90
	v_mul_lo_u32 v92, s37, v87
	v_mad_u64_u32 v[90:91], s[34:35], s36, v87, 0
	v_or_b32_e32 v87, 20, v69
	v_add3_u32 v91, v91, s23, v92
	v_mul_lo_u32 v94, s37, v87
	v_mad_u64_u32 v[92:93], s[34:35], s36, v87, 0
	v_add3_u32 v93, v93, s23, v94
	v_or_b32_e32 v87, 22, v69
	v_lshl_add_u64 v[96:97], v[92:93], 2, v[70:71]
	v_mul_lo_u32 v94, s37, v87
	v_mad_u64_u32 v[92:93], s[34:35], s36, v87, 0
	v_add3_u32 v93, v93, s23, v94
	v_or_b32_e32 v87, 24, v69
	v_lshl_add_u64 v[98:99], v[92:93], 2, v[70:71]
	v_mul_lo_u32 v94, s37, v87
	v_mad_u64_u32 v[92:93], s[34:35], s36, v87, 0
	v_add3_u32 v93, v93, s23, v94
	v_or_b32_e32 v87, 26, v69
	v_lshl_add_u64 v[100:101], v[92:93], 2, v[70:71]
	v_mul_lo_u32 v94, s37, v87
	v_mad_u64_u32 v[92:93], s[34:35], s36, v87, 0
	v_add3_u32 v93, v93, s23, v94
	v_or_b32_e32 v87, 28, v69
	v_lshl_add_u64 v[102:103], v[92:93], 2, v[70:71]
	v_mul_lo_u32 v94, s37, v87
	v_mad_u64_u32 v[92:93], s[34:35], s36, v87, 0
	v_add3_u32 v93, v93, s23, v94
	v_or_b32_e32 v87, 30, v69
	v_lshl_add_u64 v[104:105], v[92:93], 2, v[70:71]
	v_mul_lo_u32 v94, s37, v87
	v_mad_u64_u32 v[92:93], s[34:35], s36, v87, 0
	v_lshl_add_u64 v[88:89], v[88:89], 2, v[70:71]
	v_lshl_add_u64 v[90:91], v[90:91], 2, v[70:71]
	v_add3_u32 v93, v93, s23, v94
	v_or_b32_e32 v95, 32, v69
	v_lshl_add_u64 v[106:107], v[92:93], 2, v[70:71]
	global_load_dword v94, v[88:89], off
	global_load_dword v93, v[90:91], off
	global_load_dword v92, v[96:97], off
	s_nop 0
	global_load_dword v91, v[98:99], off
	global_load_dword v90, v[100:101], off
	global_load_dword v89, v[102:103], off
	global_load_dword v88, v[104:105], off
	global_load_dword v87, v[106:107], off
	v_mul_lo_u32 v98, s37, v95
	v_mad_u64_u32 v[96:97], s[34:35], s36, v95, 0
	v_or_b32_e32 v95, 34, v69
	v_add3_u32 v97, v97, s23, v98
	v_mul_lo_u32 v100, s37, v95
	v_mad_u64_u32 v[98:99], s[34:35], s36, v95, 0
	v_or_b32_e32 v95, 36, v69
	v_add3_u32 v99, v99, s23, v100
	v_mul_lo_u32 v102, s37, v95
	v_mad_u64_u32 v[100:101], s[34:35], s36, v95, 0
	v_add3_u32 v101, v101, s23, v102
	v_or_b32_e32 v95, 38, v69
	v_lshl_add_u64 v[104:105], v[100:101], 2, v[70:71]
	v_mul_lo_u32 v102, s37, v95
	v_mad_u64_u32 v[100:101], s[34:35], s36, v95, 0
	v_add3_u32 v101, v101, s23, v102
	v_or_b32_e32 v95, 40, v69
	v_lshl_add_u64 v[106:107], v[100:101], 2, v[70:71]
	v_mul_lo_u32 v102, s37, v95
	v_mad_u64_u32 v[100:101], s[34:35], s36, v95, 0
	v_add3_u32 v101, v101, s23, v102
	v_or_b32_e32 v95, 42, v69
	v_lshl_add_u64 v[108:109], v[100:101], 2, v[70:71]
	v_mul_lo_u32 v102, s37, v95
	v_mad_u64_u32 v[100:101], s[34:35], s36, v95, 0
	v_add3_u32 v101, v101, s23, v102
	v_or_b32_e32 v95, 44, v69
	v_lshl_add_u64 v[110:111], v[100:101], 2, v[70:71]
	v_mul_lo_u32 v102, s37, v95
	v_mad_u64_u32 v[100:101], s[34:35], s36, v95, 0
	v_add3_u32 v101, v101, s23, v102
	v_or_b32_e32 v95, 46, v69
	v_lshl_add_u64 v[112:113], v[100:101], 2, v[70:71]
	v_mul_lo_u32 v102, s37, v95
	v_mad_u64_u32 v[100:101], s[34:35], s36, v95, 0
	v_lshl_add_u64 v[96:97], v[96:97], 2, v[70:71]
	v_lshl_add_u64 v[98:99], v[98:99], 2, v[70:71]
	v_add3_u32 v101, v101, s23, v102
	v_or_b32_e32 v103, 48, v69
	v_lshl_add_u64 v[114:115], v[100:101], 2, v[70:71]
	global_load_dword v102, v[96:97], off
	global_load_dword v101, v[98:99], off
	global_load_dword v100, v[104:105], off
	s_nop 0
	global_load_dword v99, v[106:107], off
	global_load_dword v98, v[108:109], off
	global_load_dword v97, v[110:111], off
	global_load_dword v96, v[112:113], off
	global_load_dword v95, v[114:115], off
	v_mul_lo_u32 v106, s37, v103
	v_mad_u64_u32 v[104:105], s[34:35], s36, v103, 0
	v_or_b32_e32 v103, 50, v69
	v_add3_u32 v105, v105, s23, v106
	v_mul_lo_u32 v108, s37, v103
	v_mad_u64_u32 v[106:107], s[34:35], s36, v103, 0
	v_or_b32_e32 v103, 52, v69
	v_add3_u32 v107, v107, s23, v108
	v_mul_lo_u32 v110, s37, v103
	v_mad_u64_u32 v[108:109], s[34:35], s36, v103, 0
	v_add3_u32 v109, v109, s23, v110
	v_or_b32_e32 v103, 54, v69
	v_lshl_add_u64 v[110:111], v[108:109], 2, v[70:71]
	v_mul_lo_u32 v112, s37, v103
	v_mad_u64_u32 v[108:109], s[34:35], s36, v103, 0
	v_add3_u32 v109, v109, s23, v112
	v_or_b32_e32 v103, 56, v69
	v_lshl_add_u64 v[112:113], v[108:109], 2, v[70:71]
	v_mul_lo_u32 v114, s37, v103
	v_mad_u64_u32 v[108:109], s[34:35], s36, v103, 0
	v_add3_u32 v109, v109, s23, v114
	v_or_b32_e32 v103, 58, v69
	v_lshl_add_u64 v[114:115], v[108:109], 2, v[70:71]
	v_mul_lo_u32 v116, s37, v103
	v_mad_u64_u32 v[108:109], s[34:35], s36, v103, 0
	v_add3_u32 v109, v109, s23, v116
	v_or_b32_e32 v103, 60, v69
	v_lshl_add_u64 v[116:117], v[108:109], 2, v[70:71]
	v_mul_lo_u32 v118, s37, v103
	v_mad_u64_u32 v[108:109], s[34:35], s36, v103, 0
	v_add3_u32 v109, v109, s23, v118
	v_or_b32_e32 v69, 62, v69
	v_lshl_add_u64 v[118:119], v[108:109], 2, v[70:71]
	v_mul_lo_u32 v103, s37, v69
	v_mad_u64_u32 v[108:109], s[34:35], s36, v69, 0
	v_lshl_add_u64 v[104:105], v[104:105], 2, v[70:71]
	v_lshl_add_u64 v[106:107], v[106:107], 2, v[70:71]
	v_add3_u32 v109, v109, s23, v103
	v_lshl_add_u64 v[120:121], v[108:109], 2, v[70:71]
	global_load_dword v108, v[104:105], off
	s_nop 0
	global_load_dword v107, v[106:107], off
	s_nop 0
	global_load_dword v106, v[110:111], off
	global_load_dword v105, v[112:113], off
	global_load_dword v104, v[114:115], off
	global_load_dword v103, v[116:117], off
	global_load_dword v71, v[118:119], off
	global_load_dword v70, v[120:121], off
	s_waitcnt vmcnt(32) lgkmcnt(0)
	s_branch .Lcvt_go_p0
.LBB0_117:
	s_waitcnt vmcnt(0) lgkmcnt(0)
.Lcvt_go_p0:
	v_add_u32_e32 v69, 0x400, v78
	ds_write2_b32 v78, v2, v3 offset1:66
	ds_write2_b32 v78, v4, v5 offset0:132 offset1:198
	ds_write2_b32 v69, v6, v7 offset0:8 offset1:74
	ds_write2_b32 v69, v8, v9 offset0:140 offset1:206
	v_add_u32_e32 v69, 0x800, v78
	ds_write2_b32 v69, v10, v11 offset0:16 offset1:82
	ds_write2_b32 v69, v12, v13 offset0:148 offset1:214
	v_add_u32_e32 v69, 0xc00, v78
	ds_write2_b32 v69, v14, v15 offset0:24 offset1:90
	ds_write2_b32 v69, v16, v17 offset0:156 offset1:222
	v_add_u32_e32 v69, 0x1000, v78
	ds_write2_b32 v69, v18, v19 offset0:32 offset1:98
	ds_write2_b32 v69, v20, v21 offset0:164 offset1:230
	v_add_u32_e32 v69, 0x1400, v78
	ds_write2_b32 v69, v22, v23 offset0:40 offset1:106
	ds_write2_b32 v69, v24, v25 offset0:172 offset1:238
	v_add_u32_e32 v69, 0x1800, v78
	ds_write2_b32 v69, v26, v27 offset0:48 offset1:114
	ds_write2_b32 v69, v28, v29 offset0:180 offset1:246
	v_add_u32_e32 v69, 0x1c00, v78
	ds_write2_b32 v69, v30, v31 offset0:56 offset1:122
	ds_write2_b32 v69, v32, v33 offset0:188 offset1:254
	s_waitcnt lgkmcnt(0)
	ds_read2_b32 v[114:115], v74 offset1:8
	ds_read2_b32 v[116:117], v74 offset0:33 offset1:41
	ds_read2_b32 v[118:119], v74 offset0:66 offset1:74
	ds_read2_b32 v[120:121], v74 offset0:99 offset1:107
	ds_read2_b32 v[122:123], v74 offset0:132 offset1:140
	s_waitcnt lgkmcnt(4)
	v_bfe_u32 v69, v114, 16, 1
	v_add3_u32 v69, v114, v69, s59
	s_waitcnt lgkmcnt(3)
	v_bfe_u32 v109, v116, 16, 1
	v_lshrrev_b32_e32 v69, 16, v69
	v_add3_u32 v109, v116, v109, s59
	ds_read2_b32 v[124:125], v74 offset0:165 offset1:173
	v_and_or_b32 v110, v109, s60, v69
	s_waitcnt lgkmcnt(3)
	v_bfe_u32 v69, v118, 16, 1
	v_add3_u32 v69, v118, v69, s59
	s_waitcnt lgkmcnt(2)
	v_bfe_u32 v109, v120, 16, 1
	ds_read2_b32 v[126:127], v74 offset0:198 offset1:206
	v_lshrrev_b32_e32 v69, 16, v69
	v_add3_u32 v109, v120, v109, s59
	ds_read2_b32 v[128:129], v74 offset0:231 offset1:239
	v_and_or_b32 v111, v109, s60, v69
	s_waitcnt lgkmcnt(3)
	v_bfe_u32 v69, v122, 16, 1
	v_add3_u32 v69, v122, v69, s59
	s_waitcnt lgkmcnt(2)
	v_bfe_u32 v109, v124, 16, 1
	v_lshrrev_b32_e32 v69, 16, v69
	v_add3_u32 v109, v124, v109, s59
	v_and_or_b32 v112, v109, s60, v69
	s_waitcnt lgkmcnt(1)
	v_bfe_u32 v69, v126, 16, 1
	v_add3_u32 v69, v126, v69, s59
	s_waitcnt lgkmcnt(0)
	v_bfe_u32 v109, v128, 16, 1
	v_lshrrev_b32_e32 v69, 16, v69
	v_add3_u32 v109, v128, v109, s59
	v_and_or_b32 v113, v109, s60, v69
	v_add_u32_e32 v69, s46, v73
	v_mad_u64_u32 v[130:131], s[36:37], v69, s43, 0
	v_ashrrev_i32_e32 v109, 31, v69
	v_mov_b32_e32 v114, v131
	v_mad_u64_u32 v[132:133], s[36:37], v109, s43, v[114:115]
	v_mov_b32_e32 v131, v132
	s_ashr_i32 s23, s22, 31
	v_lshl_add_u64 v[130:131], v[130:131], 1, s[20:21]
	s_lshl_b64 s[36:37], s[22:23], 1
	v_lshl_add_u64 v[130:131], v[130:131], 0, s[36:37]
	v_mov_b32_e32 v69, v67
	v_lshl_add_u64 v[130:131], v[130:131], 0, v[68:69]
	v_bfe_u32 v109, v115, 16, 1
	global_store_dwordx4 v[130:131], v[110:113], off
	v_add3_u32 v109, v115, v109, s59
	v_lshrrev_b32_e32 v109, 16, v109
	v_bfe_u32 v110, v117, 16, 1
	v_add3_u32 v110, v117, v110, s59
	v_and_or_b32 v110, v110, s60, v109
	v_bfe_u32 v109, v119, 16, 1
	v_add3_u32 v109, v119, v109, s59
	v_bfe_u32 v111, v121, 16, 1
	v_lshrrev_b32_e32 v109, 16, v109
	v_add3_u32 v111, v121, v111, s59
	v_and_or_b32 v111, v111, s60, v109
	v_bfe_u32 v109, v123, 16, 1
	v_add3_u32 v109, v123, v109, s59
	v_bfe_u32 v112, v125, 16, 1
	v_lshrrev_b32_e32 v109, 16, v109
	v_add3_u32 v112, v125, v112, s59
	v_and_or_b32 v112, v112, s60, v109
	v_bfe_u32 v109, v127, 16, 1
	v_add3_u32 v109, v127, v109, s59
	v_bfe_u32 v113, v129, 16, 1
	v_lshrrev_b32_e32 v109, 16, v109
	v_add3_u32 v113, v129, v113, s59
	v_and_or_b32 v113, v113, s60, v109
	v_add_u32_e32 v109, s46, v75
	v_mad_u64_u32 v[114:115], s[38:39], v109, s43, 0
	v_ashrrev_i32_e32 v117, 31, v109
	v_mov_b32_e32 v116, v115
	v_mad_u64_u32 v[116:117], s[38:39], v117, s43, v[116:117]
	v_mov_b32_e32 v115, v116
	v_lshl_add_u64 v[114:115], v[114:115], 1, s[20:21]
	v_lshl_add_u64 v[114:115], v[114:115], 0, s[36:37]
	ds_read2_b32 v[116:117], v74 offset0:16 offset1:24
	v_lshl_add_u64 v[114:115], v[114:115], 0, v[68:69]
	global_store_dwordx4 v[114:115], v[110:113], off
	ds_read2_b32 v[114:115], v74 offset0:49 offset1:57
	ds_read2_b32 v[118:119], v74 offset0:82 offset1:90
	ds_read2_b32 v[120:121], v74 offset0:115 offset1:123
	s_waitcnt lgkmcnt(3)
	v_bfe_u32 v109, v116, 16, 1
	v_add3_u32 v109, v116, v109, s59
	s_waitcnt lgkmcnt(2)
	v_bfe_u32 v110, v114, 16, 1
	ds_read2_b32 v[122:123], v74 offset0:148 offset1:156
	v_lshrrev_b32_e32 v109, 16, v109
	v_add3_u32 v110, v114, v110, s59
	ds_read2_b32 v[124:125], v74 offset0:181 offset1:189
	v_and_or_b32 v110, v110, s60, v109
	s_waitcnt lgkmcnt(3)
	v_bfe_u32 v109, v118, 16, 1
	v_add3_u32 v109, v118, v109, s59
	s_waitcnt lgkmcnt(2)
	v_bfe_u32 v111, v120, 16, 1
	ds_read2_b32 v[126:127], v74 offset0:214 offset1:222
	v_lshrrev_b32_e32 v109, 16, v109
	v_add3_u32 v111, v120, v111, s59
	ds_read2_b32 v[128:129], v74 offset0:247 offset1:255
	v_and_or_b32 v111, v111, s60, v109
	s_waitcnt lgkmcnt(3)
	v_bfe_u32 v109, v122, 16, 1
	v_add3_u32 v109, v122, v109, s59
	s_waitcnt lgkmcnt(2)
	v_bfe_u32 v112, v124, 16, 1
	v_lshrrev_b32_e32 v109, 16, v109
	v_add3_u32 v112, v124, v112, s59
	v_and_or_b32 v112, v112, s60, v109
	s_waitcnt lgkmcnt(1)
	v_bfe_u32 v109, v126, 16, 1
	v_add3_u32 v109, v126, v109, s59
	s_waitcnt lgkmcnt(0)
	v_bfe_u32 v113, v128, 16, 1
	v_lshrrev_b32_e32 v109, 16, v109
	v_add3_u32 v113, v128, v113, s59
	v_and_or_b32 v113, v113, s60, v109
	v_add_u32_e32 v109, s46, v76
	v_mad_u64_u32 v[130:131], s[38:39], v109, s43, 0
	v_ashrrev_i32_e32 v116, 31, v109
	v_mov_b32_e32 v114, v131
	v_mad_u64_u32 v[132:133], s[38:39], v116, s43, v[114:115]
	v_mov_b32_e32 v131, v132
	v_lshl_add_u64 v[130:131], v[130:131], 1, s[20:21]
	v_lshl_add_u64 v[130:131], v[130:131], 0, s[36:37]
	v_lshl_add_u64 v[130:131], v[130:131], 0, v[68:69]
	v_bfe_u32 v109, v117, 16, 1
	global_store_dwordx4 v[130:131], v[110:113], off
	v_add3_u32 v109, v117, v109, s59
	v_lshrrev_b32_e32 v109, 16, v109
	v_bfe_u32 v110, v115, 16, 1
	v_add3_u32 v110, v115, v110, s59
	v_and_or_b32 v110, v110, s60, v109
	v_bfe_u32 v109, v119, 16, 1
	v_add3_u32 v109, v119, v109, s59
	v_bfe_u32 v111, v121, 16, 1
	v_lshrrev_b32_e32 v109, 16, v109
	v_add3_u32 v111, v121, v111, s59
	v_and_or_b32 v111, v111, s60, v109
	v_bfe_u32 v109, v123, 16, 1
	v_add3_u32 v109, v123, v109, s59
	v_bfe_u32 v112, v125, 16, 1
	v_lshrrev_b32_e32 v109, 16, v109
	v_add3_u32 v112, v125, v112, s59
	v_and_or_b32 v112, v112, s60, v109
	v_bfe_u32 v109, v127, 16, 1
	v_add3_u32 v109, v127, v109, s59
	v_bfe_u32 v113, v129, 16, 1
	v_lshrrev_b32_e32 v109, 16, v109
	v_add3_u32 v113, v129, v113, s59
	v_and_or_b32 v113, v113, s60, v109
	v_add_u32_e32 v109, s46, v77
	v_mad_u64_u32 v[114:115], s[38:39], v109, s43, 0
	v_ashrrev_i32_e32 v117, 31, v109
	v_mov_b32_e32 v116, v115
	v_mad_u64_u32 v[116:117], s[38:39], v117, s43, v[116:117]
	v_mov_b32_e32 v115, v116
	v_lshl_add_u64 v[114:115], v[114:115], 1, s[20:21]
	v_lshl_add_u64 v[114:115], v[114:115], 0, s[36:37]
	v_lshl_add_u64 v[114:115], v[114:115], 0, v[68:69]
	global_store_dwordx4 v[114:115], v[110:113], off
	s_waitcnt lgkmcnt(0)
	s_xor_b64 s[34:35], s[24:25], -1
	s_andn2_b64 vcc, exec, s[24:25]
	s_cbranch_vccz .LBB0_87
	s_mov_b64 s[28:29], 0
	s_andn2_b64 vcc, exec, s[34:35]
	s_mov_b64 s[24:25], s[28:29]
	s_cbranch_vccnz .LBB0_88
	s_branch .LBB0_120

.LBB0_475:
	s_and_b32 s1, s52, 3
	s_lshl_b32 s0, s1, 9
	v_lshl_or_b32 v172, v141, 2, s0
	v_lshl_add_u64 v[2:3], s[28:29], 0, v[172:173]
	v_add_co_u32_e32 v4, vcc, 0x1000, v2
	s_movk_i32 s18, 0x5000
	s_nop 0
	v_addc_co_u32_e32 v5, vcc, 0, v3, vcc
	v_add_co_u32_e32 v6, vcc, s5, v2
	s_mov_b64 s[34:35], 0x2000
	s_nop 0
	v_addc_co_u32_e32 v7, vcc, 0, v3, vcc
	v_add_co_u32_e32 v8, vcc, s87, v2
	s_nop 1
	v_addc_co_u32_e32 v9, vcc, 0, v3, vcc
	flat_load_dword v52, v[2:3]
	flat_load_dword v54, v[2:3] offset:2048
	flat_load_dword v50, v[4:5]
	flat_load_dword v16, v[4:5] offset:2048
	flat_load_dword v53, v[6:7]
	flat_load_dword v55, v[6:7] offset:2048
	flat_load_dword v51, v[8:9]
	flat_load_dword v17, v[8:9] offset:2048
	v_add_co_u32_e32 v4, vcc, s6, v2
	s_nop 1
	v_addc_co_u32_e32 v5, vcc, 0, v3, vcc
	v_add_co_u32_e32 v6, vcc, s18, v2
	s_add_u32 s18, s20, s48
	s_nop 0
	v_addc_co_u32_e32 v7, vcc, 0, v3, vcc
	v_add_co_u32_e32 v18, vcc, s7, v2
	s_addc_u32 s19, s11, s49
	s_nop 0
	v_addc_co_u32_e32 v19, vcc, 0, v3, vcc
	v_add_co_u32_e32 v2, vcc, s16, v2
	s_nop 1
	v_addc_co_u32_e32 v3, vcc, 0, v3, vcc
	flat_load_dword v12, v[4:5]
	flat_load_dword v14, v[4:5] offset:2048
	flat_load_dword v10, v[6:7]
	flat_load_dword v8, v[6:7] offset:2048
	flat_load_dword v13, v[18:19]
	flat_load_dword v15, v[18:19] offset:2048
	flat_load_dword v11, v[2:3]
	flat_load_dword v9, v[2:3] offset:2048
	v_lshl_add_u64 v[2:3], s[22:23], 0, v[172:173]
	v_mov_b32_e32 v4, v170
	flat_load_dword v75, v[2:3]
	s_nop 0
	v_ashrrev_i32_e32 v5, 3, v4
	v_and_b32_e32 v2, -4, v5
	v_ashrrev_i32_e32 v3, 31, v2
	v_lshlrev_b32_e32 v4, 2, v4
	v_lshlrev_b64 v[2:3], 10, v[2:3]
	v_and_b32_e32 v6, 0x7c, v4
	v_or_b32_e32 v4, 3, v5
	v_or_b32_e32 v2, v2, v6
	v_ashrrev_i32_e32 v5, 31, v4
	v_lshl_add_u64 v[2:3], s[18:19], 0, v[2:3]
	v_lshlrev_b64 v[4:5], 10, v[4:5]
	v_or_b32_e32 v4, v4, v6
	v_add_co_u32_e32 v22, vcc, s5, v2
	v_lshl_add_u64 v[4:5], s[18:19], 0, v[4:5]
	s_nop 0
	v_addc_co_u32_e32 v23, vcc, 0, v3, vcc
	v_add_co_u32_e32 v24, vcc, s5, v4
	v_lshl_add_u64 v[6:7], v[2:3], 0, s[34:35]
	s_nop 0
	v_addc_co_u32_e32 v25, vcc, 0, v5, vcc
	v_add_co_u32_e32 v26, vcc, s6, v2
	s_mov_b64 s[18:19], 0x4000
	s_nop 0
	v_addc_co_u32_e32 v27, vcc, 0, v3, vcc
	v_add_co_u32_e32 v28, vcc, s6, v4
	flat_load_dword v18, v[2:3]
	flat_load_dword v19, v[2:3] offset:1024
	flat_load_dword v20, v[2:3] offset:2048
	flat_load_dword v21, v[4:5]
	s_nop 0
	flat_load_dword v22, v[22:23]
	s_nop 0
	flat_load_dword v23, v[6:7] offset:1024
	s_nop 0
	flat_load_dword v25, v[24:25]
	s_nop 0
	flat_load_dword v24, v[6:7] offset:2048
	v_addc_co_u32_e32 v29, vcc, 0, v5, vcc
	v_add_co_u32_e32 v32, vcc, s7, v2
	v_lshl_add_u64 v[6:7], v[2:3], 0, s[18:19]
	s_nop 0
	v_addc_co_u32_e32 v33, vcc, 0, v3, vcc
	s_mov_b64 s[18:19], 0x6000
	v_add_co_u32_e32 v4, vcc, s7, v4
	v_lshl_add_u64 v[34:35], v[2:3], 0, s[18:19]
	s_nop 0
	v_addc_co_u32_e32 v5, vcc, 0, v5, vcc
	s_mov_b64 s[18:19], 0x8000
	flat_load_dword v26, v[26:27]
	s_nop 0
	flat_load_dword v27, v[6:7] offset:1024
	flat_load_dword v31, v[28:29]
	s_nop 0
	flat_load_dword v28, v[32:33]
	flat_load_dword v29, v[34:35] offset:1024
	s_nop 0
	flat_load_dword v33, v[4:5]
	flat_load_dword v32, v[34:35] offset:2048
	flat_load_dword v30, v[6:7] offset:2048
	v_lshl_add_u64 v[4:5], v[2:3], 0, s[18:19]
	s_mov_b32 s18, 0x8000
	v_add_co_u32_e32 v6, vcc, s18, v2
	s_mov_b64 s[18:19], 0xa000
	s_nop 0
	v_addc_co_u32_e32 v7, vcc, 0, v3, vcc
	v_lshl_add_u64 v[42:43], v[2:3], 0, s[18:19]
	s_mov_b32 s18, 0xa000
	v_add_co_u32_e32 v38, vcc, s18, v2
	s_mov_b64 s[18:19], 0xc000
	s_nop 0
	v_addc_co_u32_e32 v39, vcc, 0, v3, vcc
	flat_load_dword v34, v[6:7]
	flat_load_dword v35, v[4:5] offset:1024
	flat_load_dword v36, v[4:5] offset:2048
	s_nop 0
	flat_load_dword v38, v[38:39]
	s_nop 0
	flat_load_dword v39, v[42:43] offset:1024
	flat_load_dword v40, v[42:43] offset:2048
	flat_load_dword v41, v[42:43] offset:3072
	flat_load_dword v37, v[4:5] offset:3072
	v_lshl_add_u64 v[4:5], v[2:3], 0, s[18:19]
	v_add_co_u32_e32 v6, vcc, s2, v2
	s_mov_b64 s[18:19], 0xe000
	s_nop 0
	v_addc_co_u32_e32 v7, vcc, 0, v3, vcc
	v_lshl_add_u64 v[56:57], v[2:3], 0, s[18:19]
	s_mov_b32 s18, 0xe000
	v_add_co_u32_e32 v46, vcc, s18, v2
	s_mov_b64 s[18:19], 0x10000
	s_nop 0
	v_addc_co_u32_e32 v47, vcc, 0, v3, vcc
	flat_load_dword v42, v[6:7]
	flat_load_dword v43, v[4:5] offset:1024
	flat_load_dword v44, v[4:5] offset:2048
	s_nop 0
	flat_load_dword v46, v[46:47]
	s_nop 0
	flat_load_dword v47, v[56:57] offset:1024
	flat_load_dword v48, v[56:57] offset:2048
	flat_load_dword v49, v[56:57] offset:3072
	flat_load_dword v45, v[4:5] offset:3072
	v_lshl_add_u64 v[4:5], v[2:3], 0, s[18:19]
	v_add_co_u32_e32 v6, vcc, s97, v2
	s_mov_b64 s[18:19], 0x12000
	s_nop 0
	v_addc_co_u32_e32 v7, vcc, 0, v3, vcc
	v_lshl_add_u64 v[56:57], v[2:3], 0, s[18:19]
	s_mov_b32 s18, 0x12000
	v_add_co_u32_e32 v58, vcc, s18, v2
	s_mov_b64 s[18:19], 0x14000
	s_nop 0
	v_addc_co_u32_e32 v59, vcc, 0, v3, vcc
	flat_load_dword v106, v[6:7]
	flat_load_dword v107, v[4:5] offset:1024
	flat_load_dword v108, v[4:5] offset:2048
	flat_load_dword v110, v[58:59]
	flat_load_dword v111, v[56:57] offset:1024
	flat_load_dword v112, v[56:57] offset:2048
	flat_load_dword v113, v[56:57] offset:3072
	flat_load_dword v109, v[4:5] offset:3072
	v_add_co_u32_e32 v6, vcc, s8, v2
	v_lshl_add_u64 v[4:5], v[2:3], 0, s[18:19]
	s_nop 0
	v_addc_co_u32_e32 v7, vcc, 0, v3, vcc
	s_mov_b64 s[18:19], 0x16000
	v_add_co_u32_e32 v58, vcc, s27, v2
	v_lshl_add_u64 v[56:57], v[2:3], 0, s[18:19]
	s_nop 0
	v_addc_co_u32_e32 v59, vcc, 0, v3, vcc
	s_mov_b64 s[18:19], 0x18000
	flat_load_dword v114, v[6:7]
	flat_load_dword v115, v[4:5] offset:1024
	flat_load_dword v116, v[4:5] offset:2048
	flat_load_dword v120, v[58:59]
	flat_load_dword v121, v[56:57] offset:1024
	flat_load_dword v122, v[56:57] offset:2048
	flat_load_dword v123, v[56:57] offset:3072
	flat_load_dword v117, v[4:5] offset:3072
	v_lshl_add_u64 v[4:5], v[2:3], 0, s[18:19]
	v_add_co_u32_e32 v6, vcc, s3, v2
	s_mov_b64 s[18:19], 0x1a000
	s_nop 0
	v_addc_co_u32_e32 v7, vcc, 0, v3, vcc
	v_lshl_add_u64 v[56:57], v[2:3], 0, s[18:19]
	s_mov_b32 s18, 0x1a000
	v_add_co_u32_e32 v58, vcc, s18, v2
	s_mov_b64 s[18:19], 0x1c000
	s_nop 0
	v_addc_co_u32_e32 v59, vcc, 0, v3, vcc
	flat_load_dword v124, v[6:7]
	flat_load_dword v125, v[4:5] offset:1024
	flat_load_dword v126, v[4:5] offset:2048
	flat_load_dword v128, v[58:59]
	flat_load_dword v129, v[56:57] offset:1024
	flat_load_dword v130, v[56:57] offset:2048
	flat_load_dword v131, v[56:57] offset:3072
	flat_load_dword v127, v[4:5] offset:3072
	v_lshl_add_u64 v[4:5], v[2:3], 0, s[18:19]
	s_mov_b32 s18, 0x1c000
	v_add_co_u32_e32 v6, vcc, s18, v2
	s_mov_b64 s[18:19], 0x1e000
	s_nop 0
	v_addc_co_u32_e32 v7, vcc, 0, v3, vcc
	v_lshl_add_u64 v[56:57], v[2:3], 0, s[18:19]
	s_mov_b32 s18, 0x1e000
	v_add_co_u32_e32 v2, vcc, s18, v2
	v_mov_b32_e32 v59, v0
	s_nop 0
	v_addc_co_u32_e32 v3, vcc, 0, v3, vcc
	flat_load_dword v132, v[6:7]
	flat_load_dword v133, v[4:5] offset:1024
	flat_load_dword v134, v[4:5] offset:2048
	flat_load_dword v136, v[2:3]
	flat_load_dword v137, v[56:57] offset:1024
	flat_load_dword v138, v[56:57] offset:2048
	flat_load_dword v139, v[56:57] offset:3072
	flat_load_dword v135, v[4:5] offset:3072
	s_and_b32 s18, s21, -8
	s_ashr_i32 s19, s18, 31
	v_ashrrev_i32_e32 v66, 7, v59
	v_lshlrev_b32_e32 v63, 4, v66
	v_cmp_lt_i32_e64 s[40:41], 0, v66
	s_add_u32 s50, s18, 0x2000
	s_addc_u32 s51, s19, 0
	v_cndmask_b32_e64 v2, v63, 0, s[40:41]
	v_ashrrev_i32_e32 v3, 31, v2
	v_lshl_add_u64 v[2:3], s[50:51], 0, v[2:3]
	v_mov_b64_e32 v[4:5], s[92:93]
	v_mad_u64_u32 v[6:7], s[18:19], v2, s16, v[4:5]
	v_and_b32_e32 v62, 0x7f, v59
	v_mad_i32_i24 v7, v3, s16, v7
	s_lshl_b32 s90, s1, 8
	v_lshlrev_b32_e32 v172, 1, v62
	v_lshl_add_u64 v[2:3], v[6:7], 0, s[90:91]
	v_lshl_add_u64 v[2:3], v[2:3], 0, v[172:173]
	v_add_co_u32_e32 v2, vcc, s17, v2
	v_or_b32_e32 v102, 1, v63
	s_nop 0
	v_addc_co_u32_e32 v3, vcc, 0, v3, vcc
	v_cmp_gt_i32_e32 vcc, 8, v102
	v_or_b32_e32 v103, 2, v63
	v_or_b32_e32 v104, 3, v63
	v_cndmask_b32_e32 v6, 0, v102, vcc
	v_ashrrev_i32_e32 v7, 31, v6
	v_lshl_add_u64 v[6:7], s[50:51], 0, v[6:7]
	v_mad_u64_u32 v[56:57], s[18:19], v6, s16, v[4:5]
	v_mad_i32_i24 v57, v7, s16, v57
	v_lshl_add_u64 v[6:7], v[56:57], 0, s[90:91]
	v_lshl_add_u64 v[6:7], v[6:7], 0, v[172:173]
	v_add_co_u32_e32 v6, vcc, s17, v6
	v_or_b32_e32 v105, 4, v63
	s_nop 0
	v_addc_co_u32_e32 v7, vcc, 0, v7, vcc
	v_cmp_gt_i32_e32 vcc, 8, v103
	v_or_b32_e32 v144, 5, v63
	v_or_b32_e32 v145, 6, v63
	v_cndmask_b32_e32 v56, 0, v103, vcc
	v_ashrrev_i32_e32 v57, 31, v56
	v_lshl_add_u64 v[56:57], s[50:51], 0, v[56:57]
	v_mad_u64_u32 v[60:61], s[18:19], v56, s16, v[4:5]
	v_mad_i32_i24 v61, v57, s16, v61
	v_lshl_add_u64 v[56:57], v[60:61], 0, s[90:91]
	v_lshl_add_u64 v[56:57], v[56:57], 0, v[172:173]
	v_add_co_u32_e32 v56, vcc, s17, v56
	v_or_b32_e32 v146, 7, v63
	s_nop 0
	v_addc_co_u32_e32 v57, vcc, 0, v57, vcc
	v_cmp_gt_i32_e32 vcc, 8, v104
	v_ashrrev_i32_e32 v118, 3, v59
	v_cmp_gt_i32_e64 s[38:39], 8, v118
	v_cndmask_b32_e32 v60, 0, v104, vcc
	v_ashrrev_i32_e32 v61, 31, v60
	v_lshl_add_u64 v[60:61], s[50:51], 0, v[60:61]
	v_mad_u64_u32 v[64:65], s[18:19], v60, s16, v[4:5]
	v_mad_i32_i24 v65, v61, s16, v65
	v_lshl_add_u64 v[60:61], v[64:65], 0, s[90:91]
	v_lshl_add_u64 v[60:61], v[60:61], 0, v[172:173]
	v_add_co_u32_e32 v60, vcc, s17, v60
	v_and_b32_e32 v142, 7, v59
	s_nop 0
	v_addc_co_u32_e32 v61, vcc, 0, v61, vcc
	v_cmp_gt_i32_e32 vcc, 8, v105
	global_load_ushort v80, v[2:3], off
	global_load_ushort v81, v[2:3], off offset:1024
	global_load_ushort v78, v[6:7], off
	global_load_ushort v79, v[6:7], off offset:1024
	global_load_ushort v73, v[56:57], off
	global_load_ushort v74, v[56:57], off offset:1024
	global_load_ushort v69, v[60:61], off
	global_load_ushort v70, v[60:61], off offset:1024
	v_cndmask_b32_e32 v2, 0, v105, vcc
	v_ashrrev_i32_e32 v3, 31, v2
	v_lshl_add_u64 v[2:3], s[50:51], 0, v[2:3]
	v_mad_u64_u32 v[6:7], s[18:19], v2, s16, v[4:5]
	v_mad_i32_i24 v7, v3, s16, v7
	v_lshl_add_u64 v[2:3], v[6:7], 0, s[90:91]
	v_lshl_add_u64 v[2:3], v[2:3], 0, v[172:173]
	v_add_co_u32_e32 v2, vcc, s17, v2
	s_mov_b32 s1, s91
	s_nop 0
	v_addc_co_u32_e32 v3, vcc, 0, v3, vcc
	v_cmp_gt_i32_e32 vcc, 8, v144
	s_nop 1
	v_cndmask_b32_e32 v6, 0, v144, vcc
	v_ashrrev_i32_e32 v7, 31, v6
	v_lshl_add_u64 v[6:7], s[50:51], 0, v[6:7]
	v_mad_u64_u32 v[56:57], s[18:19], v6, s16, v[4:5]
	v_mad_i32_i24 v57, v7, s16, v57
	v_lshl_add_u64 v[6:7], v[56:57], 0, s[90:91]
	v_lshl_add_u64 v[6:7], v[6:7], 0, v[172:173]
	v_add_co_u32_e32 v6, vcc, s17, v6
	s_nop 1
	v_addc_co_u32_e32 v7, vcc, 0, v7, vcc
	v_cmp_gt_i32_e32 vcc, 8, v145
	s_nop 1
	v_cndmask_b32_e32 v56, 0, v145, vcc
	v_ashrrev_i32_e32 v57, 31, v56
	v_lshl_add_u64 v[56:57], s[50:51], 0, v[56:57]
	v_mad_u64_u32 v[60:61], s[18:19], v56, s16, v[4:5]
	v_mad_i32_i24 v61, v57, s16, v61
	v_lshl_add_u64 v[56:57], v[60:61], 0, s[90:91]
	v_lshl_add_u64 v[56:57], v[56:57], 0, v[172:173]
	v_add_co_u32_e32 v56, vcc, s17, v56
	s_nop 1
	v_addc_co_u32_e32 v57, vcc, 0, v57, vcc
	v_cmp_gt_i32_e32 vcc, 8, v146
	s_nop 1
	v_cndmask_b32_e32 v60, 0, v146, vcc
	v_ashrrev_i32_e32 v61, 31, v60
	v_lshl_add_u64 v[60:61], s[50:51], 0, v[60:61]
	v_mad_u64_u32 v[64:65], s[18:19], v60, s16, v[4:5]
	v_mad_i32_i24 v65, v61, s16, v65
	v_lshl_add_u64 v[60:61], v[64:65], 0, s[90:91]
	v_lshl_add_u64 v[60:61], v[60:61], 0, v[172:173]
	v_add_co_u32_e32 v60, vcc, s17, v60
	s_nop 1
	v_addc_co_u32_e32 v61, vcc, 0, v61, vcc
	global_load_ushort v76, v[2:3], off
	global_load_ushort v77, v[2:3], off offset:1024
	global_load_ushort v71, v[6:7], off
	global_load_ushort v72, v[6:7], off offset:1024
	global_load_ushort v67, v[56:57], off
	global_load_ushort v68, v[56:57], off offset:1024
	global_load_ushort v64, v[60:61], off
	global_load_ushort v65, v[60:61], off offset:1024
	v_cndmask_b32_e64 v2, 0, v118, s[38:39]
	v_ashrrev_i32_e32 v3, 31, v2
	v_lshl_add_u64 v[2:3], s[50:51], 0, v[2:3]
	v_mad_u64_u32 v[4:5], s[18:19], v2, s16, v[4:5]
	v_mad_i32_i24 v5, v3, s16, v5
	v_lshl_add_u64 v[2:3], v[4:5], 0, s[0:1]
	v_lshlrev_b32_e32 v4, 6, v142
	v_mov_b32_e32 v5, v173
	v_lshl_add_u64 v[2:3], v[2:3], 0, v[4:5]
	v_lshl_add_u64 v[4:5], v[2:3], 0, s[34:35]
	v_add_co_u32_e32 v2, vcc, 0x2000, v2
	s_nop 1
	v_addc_co_u32_e32 v3, vcc, 0, v3, vcc
	global_load_dwordx4 v[94:97], v[2:3], off
	global_load_dwordx4 v[82:85], v[4:5], off offset:48
	global_load_dwordx4 v[86:89], v[4:5], off offset:32
	global_load_dwordx4 v[90:93], v[4:5], off offset:16
	v_ashrrev_i32_e32 v206, 5, v59
	v_and_b32_e32 v205, 31, v59
	v_mov_b32_e32 v208, 0
	v_mov_b32_e32 v209, 0
	v_mov_b32_e32 v210, 0
	v_mov_b32_e32 v211, 0
	v_cmp_gt_i32_e32 vcc, 8, v206
	s_and_saveexec_b64 s[0:1], vcc
	s_cbranch_execz .Lgla1b_skip
	v_ashrrev_i32_e32 v207, 31, v206
	v_lshl_add_u64 v[224:225], s[50:51], 0, v[206:207]
	v_mov_b64_e32 v[226:227], s[92:93]
	v_mad_u64_u32 v[226:227], s[18:19], v224, s16, v[226:227]
	v_mad_i32_i24 v227, v225, s16, v227
	s_lshl_b32 s18, s90, 1
	s_mov_b32 s19, s91
	v_lshl_add_u64 v[224:225], v[226:227], 0, s[18:19]
	v_lshlrev_b32_e32 v226, 4, v205
	v_mov_b32_e32 v227, v173
	v_lshl_add_u64 v[224:225], v[224:225], 0, v[226:227]
	v_add_co_u32_e32 v224, vcc, 0x1000, v224
	s_nop 1
	v_addc_co_u32_e32 v225, vcc, 0, v225, vcc
	global_load_dwordx4 v[208:211], v[224:225], off offset:2048
.Lgla1b_skip:
	s_or_b64 exec, exec, s[0:1]
	v_cmp_gt_i32_e32 vcc, s4, v59
	s_and_saveexec_b64 s[0:1], vcc
	s_cbranch_execz .LBB0_479
	v_ashrrev_i32_e32 v6, 2, v59
	v_and_b32_e32 v3, 3, v59
	v_cmp_gt_i32_e32 vcc, 8, v6
	v_mov_b32_e32 v2, 0
	v_lshlrev_b32_e32 v56, 4, v3
	v_mov_b32_e32 v3, 0
	v_mov_b32_e32 v4, 0
	v_mov_b32_e32 v5, 0
	s_and_saveexec_b64 s[18:19], vcc
	s_cbranch_execz .LBB0_478
	v_ashrrev_i32_e32 v7, 31, v6
	v_lshl_add_u64 v[2:3], s[50:51], 0, v[6:7]
	v_lshlrev_b64 v[2:3], 6, v[2:3]
	v_lshl_add_u64 v[2:3], s[36:37], 0, v[2:3]
	v_mov_b32_e32 v57, v173
	v_lshl_add_u64 v[60:61], v[2:3], 0, v[56:57]
	v_add_co_u32_e32 v148, vcc, 0x90000, v60
	global_load_dwordx4 v[2:5], v[60:61], off
	s_nop 0
	v_addc_co_u32_e32 v149, vcc, 0, v61, vcc
	global_load_dwordx4 v[148:151], v[148:149], off
	v_add_co_u32_e32 v228, vcc, 0x120000, v60
	s_nop 1
	v_addc_co_u32_e32 v229, vcc, 0, v61, vcc
	global_load_dwordx4 v[230:233], v[228:229], off
	v_add_co_u32_e32 v228, vcc, 0x1b0000, v60
	s_nop 1
	v_addc_co_u32_e32 v229, vcc, 0, v61, vcc
	global_load_dwordx4 v[234:237], v[228:229], off
	s_waitcnt vmcnt(0)
	v_pk_add_f32 v[154:155], v[2:3], v[148:149]
	v_pk_add_f32 v[152:153], v[4:5], v[150:151]
	v_pk_add_f32 v[4:5], v[232:233], v[236:237]
	v_pk_add_f32 v[2:3], v[230:231], v[234:235]
	v_pk_add_f32 v[4:5], v[152:153], v[4:5]
	v_pk_add_f32 v[2:3], v[154:155], v[2:3]

.LBB0_479:
	s_or_b64 exec, exec, s[0:1]
	v_and_b32_e32 v143, 31, v59
	v_lshlrev_b32_e32 v3, 3, v143
	v_ashrrev_i32_e32 v60, 5, v59
	v_lshlrev_b32_e32 v119, 5, v142
	v_cmp_gt_i32_e32 vcc, 8, v60
	v_mov_b32_e32 v2, 0
	v_lshlrev_b32_e32 v56, 1, v3
	v_mov_b32_e32 v4, 0
	v_mov_b32_e32 v5, 0
	v_mov_b32_e32 v6, 0
	v_mov_b32_e32 v7, 0
	s_and_saveexec_b64 s[0:1], vcc
	s_cbranch_execz .LBB0_481
	v_ashrrev_i32_e32 v61, 31, v60
	v_lshl_add_u64 v[4:5], s[50:51], 0, v[60:61]
	v_mov_b64_e32 v[6:7], s[92:93]
	v_mad_u64_u32 v[6:7], s[18:19], v4, s16, v[6:7]
	v_mad_i32_i24 v7, v5, s16, v7
	s_lshl_b32 s18, s90, 1
	s_mov_b32 s19, s91
	v_lshl_add_u64 v[4:5], v[6:7], 0, s[18:19]
	v_mov_b32_e32 v57, v173
	v_lshl_add_u64 v[4:5], v[4:5], 0, v[56:57]
	v_add_co_u32_e32 v4, vcc, 0x1000, v4
	s_nop 1
	v_addc_co_u32_e32 v5, vcc, 0, v5, vcc
	s_waitcnt vmcnt(0)
	v_mov_b32_e32 v4, v208
	v_mov_b32_e32 v5, v209
	v_mov_b32_e32 v6, v210
	v_mov_b32_e32 v7, v211

.LBB0_531:
	v_lshlrev_b32_e32 v6, 2, v59
	v_bfe_u32 v4, v59, 2, 2
	v_and_b32_e32 v5, 16, v59
	v_and_b32_e32 v6, 12, v6
	v_lshl_or_b32 v4, v50, 3, v4
	v_or3_b32 v5, v5, v6, s96
	v_lshlrev_b32_e32 v5, 1, v5
	v_mul_u32_u24_e32 v4, 0x210, v4
	v_add3_u32 v4, 0, v5, v4
	v_mul_u32_u24_e32 v8, 0x90, v143
	v_add_u32_e32 v6, 0xf400, v4
	v_add3_u32 v12, 0, v8, v3
	s_waitcnt lgkmcnt(0)
	s_barrier
	ds_read_b64_tr_b16 v[102:103], v4 offset:62464
	ds_read_b64_tr_b16 v[104:105], v4 offset:64576
	ds_read_b64_tr_b16 v[4:5], v6 offset:8448
	ds_read_b64_tr_b16 v[6:7], v6 offset:10560
	ds_read_b128 v[8:11], v12 offset:53248
	s_waitcnt lgkmcnt(0)
	v_mfma_f32_32x32x16_bf16 v[66:81], v[8:11], v[102:105], 0
	ds_read_b128 v[8:11], v12 offset:53280
	v_add_u32_e32 v145, 0, v3
	v_add_u32_e32 v146, 0x19000, v145
	v_readlane_b32 s0, v244, 17
	s_waitcnt lgkmcnt(0)
	v_mfma_f32_32x32x16_bf16 v[66:81], v[8:11], v[4:7], v[66:81]
	v_add_u32_e32 v10, v145, v2
	v_cvt_pk_bf16_f32 v2, v18, v19
	v_cvt_pk_bf16_f32 v3, v20, v21
	v_cvt_pk_bf16_f32 v4, v22, v23
	v_cvt_pk_bf16_f32 v5, v24, v25
	ds_read_b128 v[6:9], v10
	s_waitcnt lgkmcnt(0)
	v_mfma_f32_32x32x16_bf16 v[66:81], v[6:9], v[2:5], v[66:81]
	v_cvt_pk_bf16_f32 v2, v26, v27
	v_cvt_pk_bf16_f32 v3, v30, v31
	v_cvt_pk_bf16_f32 v4, v28, v29
	v_cvt_pk_bf16_f32 v5, v32, v33
	ds_read_b128 v[6:9], v10 offset:32
	v_mad_u32_u24 v145, v143, s86, v145
	s_waitcnt lgkmcnt(0)
	v_mfma_f32_32x32x16_bf16 v[66:81], v[6:9], v[2:5], v[66:81]
	v_cvt_pk_bf16_f32 v2, v34, v35
	v_cvt_pk_bf16_f32 v3, v36, v37
	v_cvt_pk_bf16_f32 v4, v38, v39
	v_cvt_pk_bf16_f32 v5, v40, v41
	ds_read_b128 v[6:9], v10 offset:64
	s_waitcnt lgkmcnt(0)
	v_mfma_f32_32x32x16_bf16 v[66:81], v[6:9], v[2:5], v[66:81]
	v_cvt_pk_bf16_f32 v2, v42, v43
	v_cvt_pk_bf16_f32 v3, v44, v45
	v_cvt_pk_bf16_f32 v4, v46, v47
	v_cvt_pk_bf16_f32 v5, v48, v49
	ds_read_b128 v[6:9], v10 offset:96
	s_waitcnt lgkmcnt(0)
	v_mfma_f32_32x32x16_bf16 v[66:81], v[6:9], v[2:5], v[66:81]
	v_cvt_pk_bf16_f32 v2, v106, v107
	v_cvt_pk_bf16_f32 v3, v108, v109
	v_cvt_pk_bf16_f32 v4, v110, v111
	v_cvt_pk_bf16_f32 v5, v112, v113
	ds_read_b128 v[6:9], v10 offset:128
	s_waitcnt lgkmcnt(0)
	v_mfma_f32_32x32x16_bf16 v[66:81], v[6:9], v[2:5], v[66:81]
	v_cvt_pk_bf16_f32 v2, v114, v115
	v_cvt_pk_bf16_f32 v3, v116, v117
	v_cvt_pk_bf16_f32 v4, v120, v121
	v_cvt_pk_bf16_f32 v5, v122, v123
	ds_read_b128 v[6:9], v10 offset:160
	s_waitcnt lgkmcnt(0)
	v_mfma_f32_32x32x16_bf16 v[66:81], v[6:9], v[2:5], v[66:81]
	v_cvt_pk_bf16_f32 v2, v124, v125
	v_cvt_pk_bf16_f32 v3, v126, v127
	v_cvt_pk_bf16_f32 v4, v128, v129
	v_cvt_pk_bf16_f32 v5, v130, v131
	ds_read_b128 v[6:9], v10 offset:192
	s_waitcnt lgkmcnt(0)
	v_mfma_f32_32x32x16_bf16 v[66:81], v[6:9], v[2:5], v[66:81]
	v_cvt_pk_bf16_f32 v2, v132, v133
	v_cvt_pk_bf16_f32 v3, v134, v135
	v_cvt_pk_bf16_f32 v4, v136, v137
	v_cvt_pk_bf16_f32 v5, v138, v139
	ds_read_b128 v[6:9], v10 offset:224
	s_waitcnt lgkmcnt(0)
	v_mfma_f32_32x32x16_bf16 v[66:81], v[6:9], v[2:5], v[66:81]
	s_nop 0
	s_nop 7
	s_nop 3
	ds_read_b128 v[2:5], v146
	ds_read_b128 v[6:9], v146 offset:32
	ds_read_b128 v[10:13], v146 offset:64
	ds_read_b128 v[14:17], v146 offset:96
	s_waitcnt lgkmcnt(3)
	v_pk_mul_f32 v[50:51], v[18:19], v[2:3]
	v_pk_mul_f32 v[52:53], v[20:21], v[4:5]
	ds_read_b128 v[2:5], v145 offset:34816
	s_waitcnt lgkmcnt(3)
	v_pk_mul_f32 v[54:55], v[22:23], v[6:7]
	v_pk_mul_f32 v[56:57], v[24:25], v[8:9]
	s_waitcnt lgkmcnt(2)
	v_pk_mul_f32 v[58:59], v[26:27], v[10:11]
	v_pk_mul_f32 v[60:61], v[30:31], v[12:13]
	s_waitcnt lgkmcnt(1)
	v_pk_mul_f32 v[62:63], v[28:29], v[14:15]
	v_pk_mul_f32 v[64:65], v[32:33], v[16:17]
	s_waitcnt lgkmcnt(0)
	s_nop 0
	v_mfma_f32_32x32x16_bf16 v[50:65], v[2:5], v[102:105], v[50:65]
	s_nop 0
	s_nop 7
	s_nop 3
	ds_read_b128 v[2:5], v146 offset:128
	ds_read_b128 v[6:9], v146 offset:160
	ds_read_b128 v[10:13], v146 offset:192
	ds_read_b128 v[14:17], v146 offset:224
	s_waitcnt lgkmcnt(3)
	v_pk_mul_f32 v[34:35], v[34:35], v[2:3]
	v_pk_mul_f32 v[36:37], v[36:37], v[4:5]
	ds_read_b128 v[2:5], v145 offset:39424
	s_waitcnt lgkmcnt(3)
	v_pk_mul_f32 v[38:39], v[38:39], v[6:7]
	v_pk_mul_f32 v[40:41], v[40:41], v[8:9]
	s_waitcnt lgkmcnt(2)
	v_pk_mul_f32 v[42:43], v[42:43], v[10:11]
	v_pk_mul_f32 v[44:45], v[44:45], v[12:13]
	s_waitcnt lgkmcnt(1)
	v_pk_mul_f32 v[46:47], v[46:47], v[14:15]
	v_pk_mul_f32 v[48:49], v[48:49], v[16:17]
	s_waitcnt lgkmcnt(0)
	s_nop 0
	v_mfma_f32_32x32x16_bf16 v[34:49], v[2:5], v[102:105], v[34:49]
	s_nop 0
	s_nop 7
	s_nop 3
	ds_read_b128 v[2:5], v146 offset:256
	ds_read_b128 v[6:9], v146 offset:288
	ds_read_b128 v[10:13], v146 offset:320
	ds_read_b128 v[14:17], v146 offset:352
	s_waitcnt lgkmcnt(3)
	v_pk_mul_f32 v[18:19], v[106:107], v[2:3]
	v_pk_mul_f32 v[20:21], v[108:109], v[4:5]
	ds_read_b128 v[2:5], v145 offset:44032
	s_waitcnt lgkmcnt(3)
	v_pk_mul_f32 v[22:23], v[110:111], v[6:7]
	v_pk_mul_f32 v[24:25], v[112:113], v[8:9]
	s_waitcnt lgkmcnt(2)
	v_pk_mul_f32 v[26:27], v[114:115], v[10:11]
	v_pk_mul_f32 v[28:29], v[116:117], v[12:13]
	s_waitcnt lgkmcnt(1)
	v_pk_mul_f32 v[30:31], v[120:121], v[14:15]
	v_pk_mul_f32 v[32:33], v[122:123], v[16:17]
	s_waitcnt lgkmcnt(0)
	s_nop 0
	v_mfma_f32_32x32x16_bf16 v[18:33], v[2:5], v[102:105], v[18:33]
	s_nop 0
	s_nop 7
	s_nop 3
	ds_read_b128 v[2:5], v146 offset:384
	ds_read_b128 v[6:9], v146 offset:416
	ds_read_b128 v[10:13], v146 offset:448
	ds_read_b128 v[14:17], v146 offset:480
	ds_read_b128 v[106:109], v145 offset:48640
	s_waitcnt lgkmcnt(4)
	v_pk_mul_f32 v[2:3], v[124:125], v[2:3]
	v_pk_mul_f32 v[4:5], v[126:127], v[4:5]
	s_waitcnt lgkmcnt(3)
	v_pk_mul_f32 v[6:7], v[128:129], v[6:7]
	v_pk_mul_f32 v[8:9], v[130:131], v[8:9]
	s_waitcnt lgkmcnt(2)
	v_pk_mul_f32 v[10:11], v[132:133], v[10:11]
	v_pk_mul_f32 v[12:13], v[134:135], v[12:13]
	s_waitcnt lgkmcnt(1)
	v_pk_mul_f32 v[14:15], v[136:137], v[14:15]
	v_pk_mul_f32 v[16:17], v[138:139], v[16:17]
	s_waitcnt lgkmcnt(0)
	s_nop 0
	v_mfma_f32_32x32x16_bf16 v[2:17], v[106:109], v[102:105], v[2:17]
	v_lshlrev_b32_e32 v102, 2, v143
	v_mul_i32_i24_e32 v103, 0x410, v144
	v_add3_u32 v102, s0, v102, v103
	s_movk_i32 s0, 0x410
	s_nop 7
	s_nop 3
	s_barrier
	ds_write_b32 v102, v66
	ds_write_b32 v102, v67 offset:1040
	ds_write_b32 v102, v68 offset:2080
	ds_write_b32 v102, v69 offset:3120
	ds_write_b32 v102, v70 offset:8320
	ds_write_b32 v102, v71 offset:9360
	ds_write_b32 v102, v72 offset:10400
	ds_write_b32 v102, v73 offset:11440
	ds_write_b32 v102, v74 offset:16640
	ds_write_b32 v102, v75 offset:17680
	ds_write_b32 v102, v76 offset:18720
	ds_write_b32 v102, v77 offset:19760
	ds_write_b32 v102, v78 offset:24960
	ds_write_b32 v102, v79 offset:26000
	ds_write_b32 v102, v80 offset:27040
	ds_write_b32 v102, v81 offset:28080
	v_lshlrev_b32_e32 v66, 7, v142
	v_mul_lo_u32 v67, v118, s0
	v_add3_u32 v125, 0, v66, v67
	s_waitcnt lgkmcnt(0)
	s_barrier
	ds_read_b128 v[114:117], v125
	ds_read_b128 v[110:113], v125 offset:16
	ds_read_b128 v[106:109], v125 offset:32
	ds_read_b128 v[102:105], v125 offset:48
	ds_read_b128 v[78:81], v125 offset:64
	ds_read_b128 v[74:77], v125 offset:80
	s_waitcnt lgkmcnt(5)
	v_mov_b32_e32 v66, v114
	s_waitcnt lgkmcnt(4)
	v_mov_b32_e32 v67, v110
	v_mov_b32_e32 v68, v115
	v_mov_b32_e32 v69, v111
	v_pk_add_f32 v[66:67], v[66:67], v[68:69]
	v_mov_b32_e32 v68, v116
	v_mov_b32_e32 v69, v112
	v_mov_b32_e32 v70, v117
	v_mov_b32_e32 v71, v113
	v_pk_add_f32 v[68:69], v[68:69], v[70:71]
	s_waitcnt lgkmcnt(3)
	v_mov_b32_e32 v70, v106
	v_pk_add_f32 v[66:67], v[66:67], v[68:69]
	v_mov_b32_e32 v68, v107
	v_mov_b32_e32 v69, v108
	v_mov_b32_e32 v71, v109
	v_pk_add_f32 v[68:69], v[68:69], v[70:71]
	v_add_f32_e32 v66, 0, v66
	v_pk_add_f32 v[68:69], v[68:69], v[68:69] op_sel:[0,1] op_sel_hi:[1,0]
	v_add_f32_e32 v66, v66, v67
	s_waitcnt lgkmcnt(2)
	v_add_f32_e32 v70, v102, v103
	v_add_f32_e32 v72, v104, v105
	s_waitcnt lgkmcnt(1)
	v_mov_b32_e32 v67, v78
	v_mov_b32_e32 v69, v79
	v_mov_b32_e32 v71, v80
	v_mov_b32_e32 v73, v81
	v_pk_add_f32 v[66:67], v[66:67], v[68:69]
	v_pk_add_f32 v[68:69], v[70:71], v[72:73]
	ds_read_b128 v[70:73], v125 offset:96
	v_pk_add_f32 v[66:67], v[66:67], v[68:69]
	s_waitcnt lgkmcnt(1)
	v_mov_b32_e32 v68, v74
	v_pk_add_f32 v[120:121], v[66:67], v[66:67] op_sel:[0,1] op_sel_hi:[1,0]
	v_mov_b32_e32 v66, v75
	v_mov_b32_e32 v67, v76
	v_mov_b32_e32 v69, v77
	v_pk_add_f32 v[66:67], v[66:67], v[68:69]
	s_nop 0
	v_pk_add_f32 v[122:123], v[66:67], v[66:67] op_sel:[0,1] op_sel_hi:[1,0]
	ds_read_b128 v[66:69], v125 offset:112
	s_waitcnt lgkmcnt(1)
	v_add_f32_e32 v124, v70, v71
	v_add_f32_e32 v126, v72, v73
	s_waitcnt lgkmcnt(0)
	v_mov_b32_e32 v121, v66
	v_mov_b32_e32 v123, v67
	v_mov_b32_e32 v125, v68
	v_mov_b32_e32 v127, v69
	v_pk_add_f32 v[120:121], v[120:121], v[122:123]
	v_pk_add_f32 v[122:123], v[124:125], v[126:127]
	s_nop 0
	v_pk_add_f32 v[120:121], v[120:121], v[122:123]
	v_and_b32_e32 v122, 64, v203
	v_add_f32_e32 v120, v120, v121
	v_xor_b32_e32 v121, 1, v203
	v_add_u32_e32 v122, 64, v122
	v_cmp_lt_i32_e32 vcc, v121, v122
	s_nop 1
	v_cndmask_b32_e32 v121, v203, v121, vcc
	v_lshlrev_b32_e32 v121, 2, v121
	ds_bpermute_b32 v123, v121, v120
	s_waitcnt lgkmcnt(0)
	v_add_f32_e32 v120, v120, v123
	v_xor_b32_e32 v123, 2, v203
	v_cmp_lt_i32_e32 vcc, v123, v122
	s_nop 1
	v_cndmask_b32_e32 v123, v203, v123, vcc
	v_lshlrev_b32_e32 v123, 2, v123
	ds_bpermute_b32 v124, v123, v120
	s_waitcnt lgkmcnt(0)
	v_add_f32_e32 v120, v120, v124
	v_xor_b32_e32 v124, 4, v203
	v_cmp_lt_i32_e32 vcc, v124, v122
	s_nop 1
	v_cndmask_b32_e32 v122, v203, v124, vcc
	v_lshlrev_b32_e32 v124, 2, v122
	ds_bpermute_b32 v122, v124, v120
	s_waitcnt lgkmcnt(0)
	v_add_f32_e32 v120, v120, v122
	v_fmamk_f32 v117, v120, 0xbb800000, v117
	v_fmamk_f32 v115, v120, 0xbb800000, v115
	v_fmamk_f32 v116, v120, 0xbb800000, v116
	v_fmac_f32_e32 v114, 0xbb800000, v120
	v_mul_f32_e32 v122, v115, v115
	v_mul_f32_e32 v125, v117, v117
	v_fmac_f32_e32 v122, v114, v114
	v_fmac_f32_e32 v125, v116, v116
	v_fmamk_f32 v113, v120, 0xbb800000, v113
	v_fmamk_f32 v111, v120, 0xbb800000, v111
	v_add_f32_e32 v122, v122, v125
	v_fmamk_f32 v112, v120, 0xbb800000, v112
	v_fmac_f32_e32 v110, 0xbb800000, v120
	v_mul_f32_e32 v125, v111, v111
	v_mul_f32_e32 v126, v113, v113
	v_fmac_f32_e32 v125, v110, v110
	v_fmac_f32_e32 v126, v112, v112
	v_add_f32_e32 v125, v125, v126
	v_fmamk_f32 v109, v120, 0xbb800000, v109
	v_fmamk_f32 v107, v120, 0xbb800000, v107
	v_add_f32_e32 v122, v122, v125
	v_fmamk_f32 v108, v120, 0xbb800000, v108
	v_fmac_f32_e32 v106, 0xbb800000, v120
	v_mul_f32_e32 v125, v107, v107
	v_mul_f32_e32 v126, v109, v109
	v_fmac_f32_e32 v125, v106, v106
	v_fmac_f32_e32 v126, v108, v108
	v_add_f32_e32 v125, v125, v126
	v_fmamk_f32 v105, v120, 0xbb800000, v105
	v_fmamk_f32 v103, v120, 0xbb800000, v103
	v_add_f32_e32 v122, v125, v122
	v_fmamk_f32 v104, v120, 0xbb800000, v104
	v_fmac_f32_e32 v102, 0xbb800000, v120
	v_mul_f32_e32 v125, v103, v103
	v_mul_f32_e32 v126, v105, v105
	v_fmac_f32_e32 v125, v102, v102
	v_fmac_f32_e32 v126, v104, v104
	v_add_f32_e32 v125, v125, v126
	v_fmamk_f32 v81, v120, 0xbb800000, v81
	v_fmamk_f32 v79, v120, 0xbb800000, v79
	v_add_f32_e32 v122, v125, v122
	v_fmamk_f32 v80, v120, 0xbb800000, v80
	v_fmac_f32_e32 v78, 0xbb800000, v120
	v_mul_f32_e32 v125, v79, v79
	v_mul_f32_e32 v126, v81, v81
	v_fmac_f32_e32 v125, v78, v78
	v_fmac_f32_e32 v126, v80, v80
	v_add_f32_e32 v125, v125, v126
	v_fmamk_f32 v77, v120, 0xbb800000, v77
	v_fmamk_f32 v75, v120, 0xbb800000, v75
	v_add_f32_e32 v122, v125, v122
	v_fmamk_f32 v76, v120, 0xbb800000, v76
	v_fmac_f32_e32 v74, 0xbb800000, v120
	v_mul_f32_e32 v125, v75, v75
	v_mul_f32_e32 v126, v77, v77
	v_fmac_f32_e32 v125, v74, v74
	v_fmac_f32_e32 v126, v76, v76
	v_add_f32_e32 v125, v125, v126
	v_fmamk_f32 v73, v120, 0xbb800000, v73
	v_fmamk_f32 v71, v120, 0xbb800000, v71
	v_add_f32_e32 v122, v125, v122
	v_fmamk_f32 v72, v120, 0xbb800000, v72
	v_fmac_f32_e32 v70, 0xbb800000, v120
	v_mul_f32_e32 v125, v71, v71
	v_mul_f32_e32 v126, v73, v73
	v_fmac_f32_e32 v125, v70, v70
	v_fmac_f32_e32 v126, v72, v72
	v_add_f32_e32 v125, v125, v126
	v_fmamk_f32 v69, v120, 0xbb800000, v69
	v_fmamk_f32 v67, v120, 0xbb800000, v67
	v_add_f32_e32 v122, v125, v122
	v_fmamk_f32 v68, v120, 0xbb800000, v68
	v_fmac_f32_e32 v66, 0xbb800000, v120
	v_mul_f32_e32 v120, v67, v67
	v_mul_f32_e32 v125, v69, v69
	v_fmac_f32_e32 v120, v66, v66
	v_fmac_f32_e32 v125, v68, v68
	v_add_f32_e32 v120, v120, v125
	v_add_f32_e32 v120, v120, v122
	ds_bpermute_b32 v121, v121, v120
	s_waitcnt lgkmcnt(0)
	v_add_f32_e32 v120, v120, v121
	ds_bpermute_b32 v121, v123, v120
	s_waitcnt lgkmcnt(0)
	v_add_f32_e32 v122, v120, v121
	ds_bpermute_b32 v123, v124, v122
	s_and_saveexec_b64 s[18:19], s[38:39]
	s_cbranch_execz .LBB0_474
	v_or_b32_e32 v136, s90, v119
	v_lshlrev_b32_e32 v172, 2, v136
	v_lshl_add_u64 v[120:121], s[46:47], 0, v[172:173]
	global_load_dwordx4 v[204:207], v[120:121], off
	global_load_dwordx4 v[208:211], v[120:121], off offset:16
	global_load_dwordx4 v[212:215], v[120:121], off offset:32
	global_load_dwordx4 v[216:219], v[120:121], off offset:48
	global_load_dwordx4 v[220:223], v[120:121], off offset:64
	global_load_dwordx4 v[224:227], v[120:121], off offset:80
	global_load_dwordx4 v[228:231], v[120:121], off offset:96
	global_load_dwordx4 v[232:235], v[120:121], off offset:112
	s_nop 0
	s_waitcnt lgkmcnt(0)
	v_add_f32_e32 v137, v122, v123
	v_ashrrev_i32_e32 v119, 31, v118
	v_fmamk_f32 v137, v137, 0x3b800000, v171
	v_lshlrev_b32_e32 v122, 16, v94
	v_and_b32_e32 v123, 0xffff0000, v94
	v_lshlrev_b32_e32 v132, 16, v95
	v_and_b32_e32 v133, 0xffff0000, v95
	v_lshl_add_u64 v[94:95], s[50:51], 0, v[118:119]
	v_mul_f32_e32 v118, 0x4f800000, v137
	v_cmp_gt_f32_e32 vcc, s9, v137
	v_lshlrev_b32_e32 v172, 1, v136
	v_readlane_b32 s0, v242, 48
	v_cndmask_b32_e32 v137, v137, v118, vcc
	v_sqrt_f32_e32 v138, v137
	v_readlane_b32 s1, v242, 49
	v_lshlrev_b64 v[94:95], 11, v[94:95]
	v_lshlrev_b32_e32 v134, 16, v96
	v_add_u32_e32 v136, -1, v138
	v_add_u32_e32 v139, 1, v138
	v_fma_f32 v142, -v136, v138, v137
	v_lshl_add_u64 v[118:119], s[0:1], 0, v[172:173]
	v_fma_f32 v143, -v139, v138, v137
	v_cmp_ge_f32_e64 s[0:1], 0, v142
	v_lshl_add_u64 v[94:95], v[118:119], 0, v[94:95]
	v_and_b32_e32 v135, 0xffff0000, v96
	v_cndmask_b32_e64 v136, v138, v136, s[0:1]
	v_cmp_lt_f32_e64 s[0:1], 0, v143
	v_lshlrev_b32_e32 v96, 16, v97
	v_and_b32_e32 v97, 0xffff0000, v97
	v_cndmask_b32_e64 v136, v136, v139, s[0:1]
	v_mul_f32_e32 v138, 0x37800000, v136
	v_cndmask_b32_e32 v136, v136, v138, vcc
	v_cmp_class_f32_e32 vcc, v137, v200
	s_nop 1
	v_cndmask_b32_e32 v136, v136, v137, vcc
	v_div_scale_f32 v137, s[0:1], v136, v136, 1.0
	v_rcp_f32_e32 v138, v137
	v_div_scale_f32 v118, vcc, 1.0, v136, 1.0
	v_fma_f32 v119, -v137, v138, 1.0
	v_fmac_f32_e32 v138, v119, v138
	v_mul_f32_e32 v119, v118, v138
	v_fma_f32 v139, -v137, v119, v118
	v_fmac_f32_e32 v119, v139, v138
	v_fma_f32 v118, -v137, v119, v118
	v_div_fmas_f32 v118, v118, v138, v119
	v_div_fixup_f32 v118, v118, v136, 1.0
	v_pk_mul_f32 v[112:113], v[112:113], v[118:119] op_sel_hi:[1,0]
	v_pk_mul_f32 v[110:111], v[110:111], v[118:119] op_sel_hi:[1,0]
	v_pk_mul_f32 v[116:117], v[116:117], v[118:119] op_sel_hi:[1,0]
	v_pk_mul_f32 v[114:115], v[114:115], v[118:119] op_sel_hi:[1,0]
	v_pk_mul_f32 v[108:109], v[108:109], v[118:119] op_sel_hi:[1,0]
	v_pk_mul_f32 v[106:107], v[106:107], v[118:119] op_sel_hi:[1,0]
	v_pk_mul_f32 v[104:105], v[104:105], v[118:119] op_sel_hi:[1,0]
	v_pk_mul_f32 v[102:103], v[102:103], v[118:119] op_sel_hi:[1,0]
	v_pk_mul_f32 v[80:81], v[80:81], v[118:119] op_sel_hi:[1,0]
	v_pk_mul_f32 v[76:77], v[76:77], v[118:119] op_sel_hi:[1,0]
	v_pk_mul_f32 v[74:75], v[74:75], v[118:119] op_sel_hi:[1,0]
	v_pk_mul_f32 v[78:79], v[78:79], v[118:119] op_sel_hi:[1,0]
	v_pk_mul_f32 v[68:69], v[68:69], v[118:119] op_sel_hi:[1,0]
	v_pk_mul_f32 v[66:67], v[66:67], v[118:119] op_sel_hi:[1,0]
	v_pk_mul_f32 v[72:73], v[72:73], v[118:119] op_sel_hi:[1,0]
	v_pk_mul_f32 v[70:71], v[70:71], v[118:119] op_sel_hi:[1,0]
	s_waitcnt vmcnt(0)
	v_pk_mul_f32 v[114:115], v[114:115], v[204:205]
	v_pk_mul_f32 v[110:111], v[110:111], v[208:209]
	v_pk_mul_f32 v[112:113], v[112:113], v[210:211]
	v_pk_mul_f32 v[116:117], v[116:117], v[206:207]
	v_pk_mul_f32 v[96:97], v[112:113], v[96:97]
	v_pk_mul_f32 v[112:113], v[110:111], v[134:135]
	v_pk_mul_f32 v[116:117], v[116:117], v[132:133]
	v_pk_mul_f32 v[114:115], v[114:115], v[122:123]
	v_lshlrev_b32_e32 v122, 16, v92
	v_cvt_pk_bf16_f32 v110, v114, v115
	v_cvt_pk_bf16_f32 v111, v116, v117
	v_cvt_pk_bf16_f32 v112, v112, v113
	v_cvt_pk_bf16_f32 v113, v96, v97
	global_store_dwordx4 v[94:95], v[110:113], off
	s_nop 0
	s_nop 0
	s_nop 0
	v_lshlrev_b32_e32 v96, 16, v90
	v_and_b32_e32 v97, 0xffff0000, v90
	v_lshlrev_b32_e32 v90, 16, v91
	v_and_b32_e32 v91, 0xffff0000, v91
	v_and_b32_e32 v123, 0xffff0000, v92
	v_lshlrev_b32_e32 v92, 16, v93
	v_and_b32_e32 v93, 0xffff0000, v93
	s_nop 0
	v_pk_mul_f32 v[106:107], v[106:107], v[212:213]
	v_pk_mul_f32 v[108:109], v[108:109], v[214:215]
	v_pk_mul_f32 v[102:103], v[102:103], v[216:217]
	v_pk_mul_f32 v[104:105], v[104:105], v[218:219]
	v_pk_mul_f32 v[108:109], v[108:109], v[90:91]
	v_pk_mul_f32 v[90:91], v[106:107], v[96:97]
	v_pk_mul_f32 v[96:97], v[104:105], v[92:93]
	v_pk_mul_f32 v[92:93], v[102:103], v[122:123]
	v_cvt_pk_bf16_f32 v90, v90, v91
	v_cvt_pk_bf16_f32 v91, v108, v109
	v_lshlrev_b32_e32 v106, 16, v88
	v_cvt_pk_bf16_f32 v92, v92, v93
	v_cvt_pk_bf16_f32 v93, v96, v97
	global_store_dwordx4 v[94:95], v[90:93], off offset:16
	s_nop 0
	s_nop 0
	s_nop 0
	v_lshlrev_b32_e32 v96, 16, v86
	v_and_b32_e32 v97, 0xffff0000, v86
	v_lshlrev_b32_e32 v86, 16, v87
	v_and_b32_e32 v87, 0xffff0000, v87
	v_and_b32_e32 v107, 0xffff0000, v88
	v_lshlrev_b32_e32 v88, 16, v89
	v_and_b32_e32 v89, 0xffff0000, v89
	s_nop 0
	v_pk_mul_f32 v[80:81], v[80:81], v[222:223]
	v_pk_mul_f32 v[74:75], v[74:75], v[224:225]
	v_pk_mul_f32 v[76:77], v[76:77], v[226:227]
	v_pk_mul_f32 v[78:79], v[78:79], v[220:221]
	v_pk_mul_f32 v[80:81], v[80:81], v[86:87]
	v_pk_mul_f32 v[86:87], v[76:77], v[88:89]
	v_pk_mul_f32 v[76:77], v[74:75], v[106:107]
	v_pk_mul_f32 v[78:79], v[78:79], v[96:97]
	v_lshlrev_b32_e32 v88, 16, v84
	v_cvt_pk_bf16_f32 v74, v78, v79
	v_cvt_pk_bf16_f32 v75, v80, v81
	v_cvt_pk_bf16_f32 v76, v76, v77
	v_cvt_pk_bf16_f32 v77, v86, v87
	global_store_dwordx4 v[94:95], v[74:77], off offset:32
	s_nop 0
	s_nop 0
	s_nop 0
	v_and_b32_e32 v89, 0xffff0000, v84
	v_lshlrev_b32_e32 v84, 16, v85
	v_and_b32_e32 v85, 0xffff0000, v85
	v_lshlrev_b32_e32 v86, 16, v82
	v_and_b32_e32 v87, 0xffff0000, v82
	v_lshlrev_b32_e32 v82, 16, v83
	v_and_b32_e32 v83, 0xffff0000, v83
	s_nop 0
	v_pk_mul_f32 v[70:71], v[70:71], v[228:229]
	v_pk_mul_f32 v[66:67], v[66:67], v[232:233]
	v_pk_mul_f32 v[68:69], v[68:69], v[234:235]
	v_pk_mul_f32 v[72:73], v[72:73], v[230:231]
	v_pk_mul_f32 v[74:75], v[68:69], v[84:85]
	v_pk_mul_f32 v[68:69], v[66:67], v[88:89]
	v_pk_mul_f32 v[72:73], v[72:73], v[82:83]
	v_pk_mul_f32 v[70:71], v[70:71], v[86:87]
	s_nop 0
	v_cvt_pk_bf16_f32 v66, v70, v71
	v_cvt_pk_bf16_f32 v67, v72, v73
	v_cvt_pk_bf16_f32 v68, v68, v69
	v_cvt_pk_bf16_f32 v69, v74, v75
	global_store_dwordx4 v[94:95], v[66:69], off offset:48
	s_branch .LBB0_474

.LBB0_896:
	v_readlane_b32 s0, v238, 14
	v_readlane_b32 s1, v238, 15
	s_lshl_b64 s[0:1], s[0:1], 12
	v_readlane_b32 s10, v242, 42
	s_add_u32 s0, s21, s0
	s_addc_u32 s1, s20, s1
	v_add_u32_e32 v154, s10, v145
	v_readlane_b32 s10, v242, 43
	s_or_b32 s10, s10, s38
	v_ashrrev_i32_e32 v155, 31, v154
	v_or_b32_e32 v134, s10, v144
	v_ashrrev_i32_e32 v135, 31, v134
	v_lshl_add_u64 v[150:151], v[134:135], 2, s[0:1]
	global_load_dwordx4 v[204:207], v[150:151], off
	global_load_dwordx4 v[208:211], v[150:151], off offset:16
	global_load_dwordx4 v[212:215], v[150:151], off offset:512
	global_load_dwordx4 v[216:219], v[150:151], off offset:528
	s_nop 0
	v_readlane_b32 s10, v242, 36
	v_lshlrev_b64 v[136:137], 11, v[154:155]
	v_readlane_b32 s11, v242, 37
	v_lshlrev_b64 v[152:153], 1, v[134:135]
	v_mov_b64_e32 v[156:157], s[92:93]
	v_lshl_add_u64 v[138:139], s[10:11], 0, v[136:137]
	v_lshl_add_u64 v[134:135], v[138:139], 0, v[152:153]
	v_mad_i64_i32 v[138:139], s[0:1], v154, s16, v[156:157]
	global_load_dwordx4 v[178:181], v[134:135], off
	v_lshl_add_u64 v[138:139], v[138:139], 0, v[152:153]
	global_load_dwordx4 v[182:185], v[138:139], off offset:2048
	v_or_b32_e32 v140, 16, v154
	v_ashrrev_i32_e32 v141, 31, v140
	v_readlane_b32 s14, v241, 14
	v_lshlrev_b64 v[158:159], 11, v[140:141]
	v_readlane_b32 s15, v241, 15
	v_mad_i64_i32 v[142:143], s[0:1], v140, s16, v[156:157]
	s_nop 0
	v_lshl_add_u64 v[168:169], s[14:15], 0, v[136:137]
	v_lshl_add_u64 v[136:137], s[10:11], 0, v[158:159]
	v_lshl_add_u64 v[136:137], v[136:137], 0, v[152:153]
	v_lshl_add_u64 v[194:195], v[142:143], 0, v[152:153]
	global_load_dwordx4 v[186:189], v[134:135], off offset:256
	global_load_dwordx4 v[190:193], v[138:139], off offset:2304
	global_load_dwordx4 v[146:149], v[136:137], off
	s_nop 0
	global_load_dwordx4 v[138:141], v[136:137], off offset:256
	global_load_dwordx4 v[142:145], v[194:195], off offset:2048
	s_nop 0
	global_load_dwordx4 v[134:137], v[194:195], off offset:2304
	s_waitcnt vmcnt(0) lgkmcnt(0)
	v_pk_add_f32 v[132:133], v[132:133], v[206:207]
	v_pk_add_f32 v[130:131], v[130:131], v[204:205]
	v_pk_add_f32 v[128:129], v[128:129], v[210:211]
	v_pk_add_f32 v[126:127], v[126:127], v[208:209]
	v_mul_f32_e32 v130, 0xbfb8aa3b, v130
	v_mul_f32_e32 v131, 0xbfb8aa3b, v131
	v_mul_f32_e32 v132, 0xbfb8aa3b, v132
	v_mul_f32_e32 v133, 0xbfb8aa3b, v133
	v_mul_f32_e32 v126, 0xbfb8aa3b, v126
	v_mul_f32_e32 v127, 0xbfb8aa3b, v127
	v_mul_f32_e32 v128, 0xbfb8aa3b, v128
	v_mul_f32_e32 v129, 0xbfb8aa3b, v129
	v_exp_f32_e32 v130, v130
	v_exp_f32_e32 v131, v131
	v_exp_f32_e32 v132, v132
	v_exp_f32_e32 v133, v133
	v_exp_f32_e32 v126, v126
	v_exp_f32_e32 v127, v127
	v_exp_f32_e32 v128, v128
	v_exp_f32_e32 v129, v129
	v_add_f32_e32 v130, 1.0, v130
	v_add_f32_e32 v131, 1.0, v131
	v_add_f32_e32 v132, 1.0, v132
	v_add_f32_e32 v133, 1.0, v133
	v_add_f32_e32 v155, 1.0, v126
	v_add_f32_e32 v172, 1.0, v127
	v_add_f32_e32 v194, 1.0, v128
	v_add_f32_e32 v195, 1.0, v129
	v_rcp_f32_e32 v126, v130
	v_rcp_f32_e32 v127, v131
	v_rcp_f32_e32 v128, v132
	v_rcp_f32_e32 v129, v133
	v_rcp_f32_e32 v130, v155
	v_rcp_f32_e32 v132, v194
	v_rcp_f32_e32 v133, v195
	v_rcp_f32_e32 v131, v172
	v_lshlrev_b32_e32 v160, 16, v178
	v_and_b32_e32 v161, 0xffff0000, v178
	v_lshlrev_b32_e32 v162, 16, v179
	v_and_b32_e32 v163, 0xffff0000, v179
	v_lshlrev_b32_e32 v164, 16, v180
	v_and_b32_e32 v165, 0xffff0000, v180
	v_lshlrev_b32_e32 v166, 16, v181
	v_and_b32_e32 v167, 0xffff0000, v181
	v_lshlrev_b32_e32 v178, 16, v182
	v_and_b32_e32 v179, 0xffff0000, v182
	v_lshlrev_b32_e32 v180, 16, v183
	v_and_b32_e32 v181, 0xffff0000, v183
	v_pk_mul_f32 v[128:129], v[128:129], v[162:163]
	v_pk_mul_f32 v[126:127], v[126:127], v[160:161]
	v_lshlrev_b32_e32 v182, 16, v184
	v_and_b32_e32 v183, 0xffff0000, v184
	v_lshlrev_b32_e32 v184, 16, v185
	v_and_b32_e32 v185, 0xffff0000, v185
	v_pk_mul_f32 v[132:133], v[132:133], v[166:167]
	v_pk_mul_f32 v[130:131], v[130:131], v[164:165]
	v_pk_mul_f32 v[128:129], v[128:129], v[180:181]
	v_pk_mul_f32 v[126:127], v[126:127], v[178:179]
	v_lshl_add_u64 v[160:161], v[168:169], 0, v[152:153]
	v_pk_mul_f32 v[132:133], v[132:133], v[184:185]
	v_pk_mul_f32 v[130:131], v[130:131], v[182:183]
	v_cvt_pk_bf16_f32 v126, v126, v127
	v_cvt_pk_bf16_f32 v127, v128, v129
	v_lshlrev_b32_e32 v162, 16, v186
	v_cvt_pk_bf16_f32 v128, v130, v131
	v_cvt_pk_bf16_f32 v129, v132, v133
	global_store_dwordx4 v[160:161], v[126:129], off
	s_nop 0
	s_nop 0
	s_nop 0
	v_and_b32_e32 v163, 0xffff0000, v186
	v_lshlrev_b32_e32 v164, 16, v187
	v_and_b32_e32 v165, 0xffff0000, v187
	v_lshlrev_b32_e32 v166, 16, v188
	v_and_b32_e32 v167, 0xffff0000, v188
	v_lshlrev_b32_e32 v168, 16, v189
	v_and_b32_e32 v169, 0xffff0000, v189
	v_lshlrev_b32_e32 v178, 16, v190
	v_and_b32_e32 v179, 0xffff0000, v190
	v_lshlrev_b32_e32 v180, 16, v191
	v_and_b32_e32 v181, 0xffff0000, v191
	v_lshlrev_b32_e32 v182, 16, v192
	v_and_b32_e32 v183, 0xffff0000, v192
	v_lshlrev_b32_e32 v184, 16, v193
	v_and_b32_e32 v185, 0xffff0000, v193
	s_nop 0
	v_pk_add_f32 v[124:125], v[124:125], v[214:215]
	v_pk_add_f32 v[122:123], v[122:123], v[212:213]
	v_pk_add_f32 v[120:121], v[120:121], v[218:219]
	v_pk_add_f32 v[118:119], v[118:119], v[216:217]
	v_mul_f32_e32 v122, 0xbfb8aa3b, v122
	v_mul_f32_e32 v123, 0xbfb8aa3b, v123
	v_mul_f32_e32 v124, 0xbfb8aa3b, v124
	v_mul_f32_e32 v125, 0xbfb8aa3b, v125
	v_mul_f32_e32 v118, 0xbfb8aa3b, v118
	v_mul_f32_e32 v119, 0xbfb8aa3b, v119
	v_mul_f32_e32 v120, 0xbfb8aa3b, v120
	v_mul_f32_e32 v121, 0xbfb8aa3b, v121
	v_exp_f32_e32 v122, v122
	v_exp_f32_e32 v123, v123
	v_exp_f32_e32 v124, v124
	v_exp_f32_e32 v125, v125
	v_exp_f32_e32 v118, v118
	v_exp_f32_e32 v119, v119
	v_exp_f32_e32 v120, v120
	v_exp_f32_e32 v121, v121
	v_add_f32_e32 v122, 1.0, v122
	v_add_f32_e32 v123, 1.0, v123
	v_add_f32_e32 v124, 1.0, v124
	v_add_f32_e32 v125, 1.0, v125
	v_add_f32_e32 v126, 1.0, v118
	v_add_f32_e32 v127, 1.0, v119
	v_add_f32_e32 v128, 1.0, v120
	v_add_f32_e32 v129, 1.0, v121
	v_rcp_f32_e32 v118, v122
	v_rcp_f32_e32 v119, v123
	v_rcp_f32_e32 v120, v124
	v_rcp_f32_e32 v121, v125
	v_rcp_f32_e32 v122, v126
	v_rcp_f32_e32 v124, v128
	v_rcp_f32_e32 v125, v129
	v_rcp_f32_e32 v123, v127
	v_pk_mul_f32 v[120:121], v[120:121], v[164:165]
	v_pk_mul_f32 v[118:119], v[118:119], v[162:163]
	v_pk_mul_f32 v[124:125], v[124:125], v[168:169]
	v_pk_mul_f32 v[122:123], v[122:123], v[166:167]
	v_pk_mul_f32 v[120:121], v[120:121], v[180:181]
	v_pk_mul_f32 v[118:119], v[118:119], v[178:179]
	v_pk_mul_f32 v[124:125], v[124:125], v[184:185]
	v_pk_mul_f32 v[122:123], v[122:123], v[182:183]
	v_cvt_pk_bf16_f32 v118, v118, v119
	v_cvt_pk_bf16_f32 v119, v120, v121
	v_lshlrev_b32_e32 v128, 16, v146
	v_cvt_pk_bf16_f32 v120, v122, v123
	v_cvt_pk_bf16_f32 v121, v124, v125
	global_store_dwordx4 v[160:161], v[118:121], off offset:256
	s_nop 0
	s_nop 0
	s_nop 0
	v_and_b32_e32 v129, 0xffff0000, v146
	v_lshlrev_b32_e32 v130, 16, v147
	v_and_b32_e32 v131, 0xffff0000, v147
	v_lshl_add_u64 v[118:119], s[14:15], 0, v[158:159]
	v_lshlrev_b32_e32 v132, 16, v148
	v_and_b32_e32 v133, 0xffff0000, v148
	v_lshlrev_b32_e32 v146, 16, v149
	v_and_b32_e32 v147, 0xffff0000, v149
	v_lshlrev_b32_e32 v148, 16, v142
	v_and_b32_e32 v149, 0xffff0000, v142
	v_lshlrev_b32_e32 v142, 16, v143
	v_and_b32_e32 v143, 0xffff0000, v143
	v_lshl_add_u64 v[118:119], v[118:119], 0, v[152:153]
	v_lshlrev_b32_e32 v158, 16, v144
	v_and_b32_e32 v159, 0xffff0000, v144
	v_lshlrev_b32_e32 v144, 16, v145
	v_and_b32_e32 v145, 0xffff0000, v145
	s_nop 0
	v_pk_add_f32 v[116:117], v[116:117], v[206:207]
	v_pk_add_f32 v[114:115], v[114:115], v[204:205]
	v_pk_add_f32 v[112:113], v[112:113], v[210:211]
	v_pk_add_f32 v[110:111], v[110:111], v[208:209]
	v_mul_f32_e32 v114, 0xbfb8aa3b, v114
	v_mul_f32_e32 v115, 0xbfb8aa3b, v115
	v_mul_f32_e32 v116, 0xbfb8aa3b, v116
	v_mul_f32_e32 v117, 0xbfb8aa3b, v117
	v_mul_f32_e32 v110, 0xbfb8aa3b, v110
	v_mul_f32_e32 v111, 0xbfb8aa3b, v111
	v_mul_f32_e32 v112, 0xbfb8aa3b, v112
	v_mul_f32_e32 v113, 0xbfb8aa3b, v113
	v_exp_f32_e32 v114, v114
	v_exp_f32_e32 v115, v115
	v_exp_f32_e32 v116, v116
	v_exp_f32_e32 v117, v117
	v_exp_f32_e32 v110, v110
	v_exp_f32_e32 v111, v111
	v_exp_f32_e32 v112, v112
	v_exp_f32_e32 v113, v113
	v_add_f32_e32 v114, 1.0, v114
	v_add_f32_e32 v115, 1.0, v115
	v_add_f32_e32 v116, 1.0, v116
	v_add_f32_e32 v117, 1.0, v117
	v_add_f32_e32 v120, 1.0, v110
	v_add_f32_e32 v121, 1.0, v111
	v_add_f32_e32 v122, 1.0, v112
	v_add_f32_e32 v123, 1.0, v113
	v_rcp_f32_e32 v110, v114
	v_rcp_f32_e32 v111, v115
	v_rcp_f32_e32 v112, v116
	v_rcp_f32_e32 v113, v117
	v_rcp_f32_e32 v114, v120
	v_rcp_f32_e32 v116, v122
	v_rcp_f32_e32 v117, v123
	v_rcp_f32_e32 v115, v121
	v_pk_mul_f32 v[112:113], v[112:113], v[130:131]
	v_pk_mul_f32 v[110:111], v[110:111], v[128:129]
	v_pk_mul_f32 v[116:117], v[116:117], v[146:147]
	v_pk_mul_f32 v[114:115], v[114:115], v[132:133]
	v_pk_mul_f32 v[112:113], v[112:113], v[142:143]
	v_pk_mul_f32 v[110:111], v[110:111], v[148:149]
	v_pk_mul_f32 v[116:117], v[116:117], v[144:145]
	v_pk_mul_f32 v[114:115], v[114:115], v[158:159]
	v_cvt_pk_bf16_f32 v110, v110, v111
	v_cvt_pk_bf16_f32 v111, v112, v113
	v_or_b32_e32 v124, 32, v154
	v_cvt_pk_bf16_f32 v112, v114, v115
	v_cvt_pk_bf16_f32 v113, v116, v117
	global_store_dwordx4 v[118:119], v[110:113], off
	s_nop 0
	s_nop 0
	s_nop 0
	v_ashrrev_i32_e32 v125, 31, v124
	v_lshlrev_b64 v[142:143], 11, v[124:125]
	v_lshl_add_u64 v[120:121], s[10:11], 0, v[142:143]
	v_lshl_add_u64 v[144:145], v[120:121], 0, v[152:153]
	v_lshlrev_b32_e32 v120, 16, v138
	v_and_b32_e32 v121, 0xffff0000, v138
	v_lshlrev_b32_e32 v122, 16, v139
	v_and_b32_e32 v123, 0xffff0000, v139
	v_lshlrev_b32_e32 v130, 16, v134
	v_and_b32_e32 v131, 0xffff0000, v134
	v_lshlrev_b32_e32 v126, 16, v140
	v_and_b32_e32 v127, 0xffff0000, v140
	v_lshlrev_b32_e32 v128, 16, v141
	v_and_b32_e32 v129, 0xffff0000, v141
	v_lshlrev_b32_e32 v132, 16, v135
	v_and_b32_e32 v133, 0xffff0000, v135
	v_lshlrev_b32_e32 v134, 16, v136
	v_and_b32_e32 v135, 0xffff0000, v136
	v_lshlrev_b32_e32 v136, 16, v137
	v_and_b32_e32 v137, 0xffff0000, v137
	s_nop 0
	v_pk_add_f32 v[106:107], v[106:107], v[212:213]
	v_pk_add_f32 v[108:109], v[108:109], v[214:215]
	v_pk_add_f32 v[102:103], v[102:103], v[216:217]
	v_mul_f32_e32 v106, 0xbfb8aa3b, v106
	v_mul_f32_e32 v107, 0xbfb8aa3b, v107
	v_pk_add_f32 v[104:105], v[104:105], v[218:219]
	v_mul_f32_e32 v108, 0xbfb8aa3b, v108
	v_mul_f32_e32 v109, 0xbfb8aa3b, v109
	v_mul_f32_e32 v102, 0xbfb8aa3b, v102
	v_mul_f32_e32 v103, 0xbfb8aa3b, v103
	v_exp_f32_e32 v106, v106
	v_exp_f32_e32 v107, v107
	v_mul_f32_e32 v104, 0xbfb8aa3b, v104
	v_mul_f32_e32 v105, 0xbfb8aa3b, v105
	v_exp_f32_e32 v108, v108
	v_exp_f32_e32 v109, v109
	v_exp_f32_e32 v102, v102
	v_exp_f32_e32 v103, v103
	v_exp_f32_e32 v104, v104
	v_exp_f32_e32 v105, v105
	v_add_f32_e32 v106, 1.0, v106
	v_add_f32_e32 v107, 1.0, v107
	v_add_f32_e32 v108, 1.0, v108
	v_add_f32_e32 v109, 1.0, v109
	v_add_f32_e32 v110, 1.0, v102
	v_add_f32_e32 v111, 1.0, v103
	v_rcp_f32_e32 v102, v106
	v_rcp_f32_e32 v103, v107
	v_add_f32_e32 v112, 1.0, v104
	v_add_f32_e32 v113, 1.0, v105
	v_rcp_f32_e32 v104, v108
	v_rcp_f32_e32 v105, v109
	v_rcp_f32_e32 v106, v110
	v_rcp_f32_e32 v108, v112
	v_rcp_f32_e32 v109, v113
	v_rcp_f32_e32 v107, v111
	v_pk_mul_f32 v[102:103], v[102:103], v[120:121]
	v_pk_mul_f32 v[104:105], v[104:105], v[122:123]
	v_pk_mul_f32 v[102:103], v[102:103], v[130:131]
	v_pk_mul_f32 v[108:109], v[108:109], v[128:129]
	v_pk_mul_f32 v[106:107], v[106:107], v[126:127]
	v_pk_mul_f32 v[104:105], v[104:105], v[132:133]
	v_cvt_pk_bf16_f32 v102, v102, v103
	v_pk_mul_f32 v[108:109], v[108:109], v[136:137]
	v_cvt_pk_bf16_f32 v103, v104, v105
	v_pk_mul_f32 v[106:107], v[106:107], v[134:135]
	s_nop 0
	v_cvt_pk_bf16_f32 v104, v106, v107
	v_cvt_pk_bf16_f32 v105, v108, v109
	global_store_dwordx4 v[118:119], v[102:105], off offset:256
	global_load_dwordx4 v[120:123], v[144:145], off
	v_lshl_add_u64 v[108:109], s[14:15], 0, v[142:143]
	v_mad_i64_i32 v[102:103], s[0:1], v124, s16, v[156:157]
	v_lshl_add_u64 v[102:103], v[102:103], 0, v[152:153]
	global_load_dwordx4 v[124:127], v[102:103], off offset:2048
	s_nop 0
	s_nop 0
	v_or_b32_e32 v104, 48, v154
	v_ashrrev_i32_e32 v105, 31, v104
	v_lshlrev_b64 v[118:119], 11, v[104:105]
	v_mad_i64_i32 v[106:107], s[0:1], v104, s16, v[156:157]
	v_lshl_add_u64 v[104:105], s[10:11], 0, v[118:119]
	v_lshl_add_u64 v[104:105], v[104:105], 0, v[152:153]
	v_lshl_add_u64 v[146:147], v[106:107], 0, v[152:153]
	v_lshl_add_u64 v[148:149], v[108:109], 0, v[152:153]
	global_load_dwordx4 v[136:139], v[144:145], off offset:256
	global_load_dwordx4 v[140:143], v[102:103], off offset:2304
	global_load_dwordx4 v[114:117], v[104:105], off
	global_load_dwordx4 v[106:109], v[104:105], off offset:256
	global_load_dwordx4 v[110:113], v[146:147], off offset:2048
	s_nop 0
	global_load_dwordx4 v[102:105], v[146:147], off offset:2304
	s_waitcnt vmcnt(0)
	v_lshlrev_b32_e32 v144, 16, v120
	v_and_b32_e32 v145, 0xffff0000, v120
	v_lshlrev_b32_e32 v120, 16, v121
	v_and_b32_e32 v121, 0xffff0000, v121
	s_waitcnt lgkmcnt(0)
	v_pk_add_f32 v[96:97], v[96:97], v[206:207]
	v_pk_add_f32 v[94:95], v[94:95], v[204:205]
	v_pk_add_f32 v[92:93], v[92:93], v[210:211]
	v_pk_add_f32 v[90:91], v[90:91], v[208:209]
	v_mul_f32_e32 v94, 0xbfb8aa3b, v94
	v_mul_f32_e32 v95, 0xbfb8aa3b, v95
	v_mul_f32_e32 v96, 0xbfb8aa3b, v96
	v_mul_f32_e32 v97, 0xbfb8aa3b, v97
	v_mul_f32_e32 v90, 0xbfb8aa3b, v90
	v_mul_f32_e32 v91, 0xbfb8aa3b, v91
	v_mul_f32_e32 v92, 0xbfb8aa3b, v92
	v_mul_f32_e32 v93, 0xbfb8aa3b, v93
	v_exp_f32_e32 v94, v94
	v_exp_f32_e32 v95, v95
	v_exp_f32_e32 v96, v96
	v_exp_f32_e32 v97, v97
	v_exp_f32_e32 v90, v90
	v_exp_f32_e32 v91, v91
	v_exp_f32_e32 v92, v92
	v_exp_f32_e32 v93, v93
	v_add_f32_e32 v94, 1.0, v94
	v_add_f32_e32 v95, 1.0, v95
	v_add_f32_e32 v96, 1.0, v96
	v_add_f32_e32 v97, 1.0, v97
	v_add_f32_e32 v128, 1.0, v90
	v_add_f32_e32 v129, 1.0, v91
	v_add_f32_e32 v130, 1.0, v92
	v_add_f32_e32 v131, 1.0, v93
	v_rcp_f32_e32 v90, v94
	v_rcp_f32_e32 v91, v95
	v_rcp_f32_e32 v92, v96
	v_rcp_f32_e32 v93, v97
	v_rcp_f32_e32 v94, v128
	v_rcp_f32_e32 v96, v130
	v_rcp_f32_e32 v97, v131
	v_rcp_f32_e32 v95, v129
	v_lshlrev_b32_e32 v146, 16, v122
	v_and_b32_e32 v147, 0xffff0000, v122
	v_lshlrev_b32_e32 v122, 16, v123
	v_and_b32_e32 v123, 0xffff0000, v123
	v_lshlrev_b32_e32 v158, 16, v124
	v_and_b32_e32 v159, 0xffff0000, v124
	v_lshlrev_b32_e32 v124, 16, v125
	v_and_b32_e32 v125, 0xffff0000, v125
	v_pk_mul_f32 v[92:93], v[92:93], v[120:121]
	v_pk_mul_f32 v[90:91], v[90:91], v[144:145]
	v_lshlrev_b32_e32 v160, 16, v126
	v_and_b32_e32 v161, 0xffff0000, v126
	v_lshlrev_b32_e32 v126, 16, v127
	v_and_b32_e32 v127, 0xffff0000, v127
	v_pk_mul_f32 v[96:97], v[96:97], v[122:123]
	v_pk_mul_f32 v[94:95], v[94:95], v[146:147]
	v_pk_mul_f32 v[92:93], v[92:93], v[124:125]
	v_pk_mul_f32 v[90:91], v[90:91], v[158:159]
	v_pk_mul_f32 v[96:97], v[96:97], v[126:127]
	v_pk_mul_f32 v[94:95], v[94:95], v[160:161]
	v_cvt_pk_bf16_f32 v90, v90, v91
	v_cvt_pk_bf16_f32 v91, v92, v93
	v_lshlrev_b32_e32 v120, 16, v136
	v_cvt_pk_bf16_f32 v92, v94, v95
	v_cvt_pk_bf16_f32 v93, v96, v97
	global_store_dwordx4 v[148:149], v[90:93], off
	s_nop 0
	s_nop 0
	s_nop 0
	v_and_b32_e32 v121, 0xffff0000, v136
	v_lshlrev_b32_e32 v122, 16, v137
	v_and_b32_e32 v123, 0xffff0000, v137
	v_lshlrev_b32_e32 v124, 16, v138
	v_and_b32_e32 v125, 0xffff0000, v138
	v_lshlrev_b32_e32 v126, 16, v139
	v_and_b32_e32 v127, 0xffff0000, v139
	v_lshlrev_b32_e32 v128, 16, v140
	v_and_b32_e32 v129, 0xffff0000, v140
	v_lshlrev_b32_e32 v130, 16, v141
	v_and_b32_e32 v131, 0xffff0000, v141
	v_lshlrev_b32_e32 v132, 16, v142
	v_and_b32_e32 v133, 0xffff0000, v142
	v_lshlrev_b32_e32 v134, 16, v143
	v_and_b32_e32 v135, 0xffff0000, v143
	s_nop 0
	v_pk_add_f32 v[88:89], v[88:89], v[214:215]
	v_pk_add_f32 v[86:87], v[86:87], v[212:213]
	v_pk_add_f32 v[84:85], v[84:85], v[218:219]
	v_pk_add_f32 v[82:83], v[82:83], v[216:217]
	v_mul_f32_e32 v86, 0xbfb8aa3b, v86
	v_mul_f32_e32 v87, 0xbfb8aa3b, v87
	v_mul_f32_e32 v88, 0xbfb8aa3b, v88
	v_mul_f32_e32 v89, 0xbfb8aa3b, v89
	v_mul_f32_e32 v82, 0xbfb8aa3b, v82
	v_mul_f32_e32 v83, 0xbfb8aa3b, v83
	v_mul_f32_e32 v84, 0xbfb8aa3b, v84
	v_mul_f32_e32 v85, 0xbfb8aa3b, v85
	v_exp_f32_e32 v86, v86
	v_exp_f32_e32 v87, v87
	v_exp_f32_e32 v88, v88
	v_exp_f32_e32 v89, v89
	v_exp_f32_e32 v82, v82
	v_exp_f32_e32 v83, v83
	v_exp_f32_e32 v84, v84
	v_exp_f32_e32 v85, v85
	v_add_f32_e32 v86, 1.0, v86
	v_add_f32_e32 v87, 1.0, v87
	v_add_f32_e32 v88, 1.0, v88
	v_add_f32_e32 v89, 1.0, v89
	v_add_f32_e32 v90, 1.0, v82
	v_add_f32_e32 v91, 1.0, v83
	v_add_f32_e32 v92, 1.0, v84
	v_add_f32_e32 v93, 1.0, v85
	v_rcp_f32_e32 v82, v86
	v_rcp_f32_e32 v83, v87
	v_rcp_f32_e32 v84, v88
	v_rcp_f32_e32 v85, v89
	v_rcp_f32_e32 v86, v90
	v_rcp_f32_e32 v88, v92
	v_rcp_f32_e32 v89, v93
	v_rcp_f32_e32 v87, v91
	v_pk_mul_f32 v[84:85], v[84:85], v[122:123]
	v_pk_mul_f32 v[82:83], v[82:83], v[120:121]
	v_pk_mul_f32 v[88:89], v[88:89], v[126:127]
	v_pk_mul_f32 v[86:87], v[86:87], v[124:125]
	v_pk_mul_f32 v[84:85], v[84:85], v[130:131]
	v_pk_mul_f32 v[82:83], v[82:83], v[128:129]
	v_pk_mul_f32 v[88:89], v[88:89], v[134:135]
	v_pk_mul_f32 v[86:87], v[86:87], v[132:133]
	v_cvt_pk_bf16_f32 v82, v82, v83
	v_cvt_pk_bf16_f32 v83, v84, v85
	v_lshlrev_b32_e32 v92, 16, v114
	v_cvt_pk_bf16_f32 v84, v86, v87
	v_cvt_pk_bf16_f32 v85, v88, v89
	global_store_dwordx4 v[148:149], v[82:85], off offset:256
	s_nop 0
	s_nop 0
	s_nop 0
	v_and_b32_e32 v93, 0xffff0000, v114
	v_lshlrev_b32_e32 v94, 16, v115
	v_and_b32_e32 v95, 0xffff0000, v115
	v_lshl_add_u64 v[82:83], s[14:15], 0, v[118:119]
	v_lshlrev_b32_e32 v96, 16, v116
	v_and_b32_e32 v97, 0xffff0000, v116
	v_lshlrev_b32_e32 v114, 16, v117
	v_and_b32_e32 v115, 0xffff0000, v117
	v_lshlrev_b32_e32 v116, 16, v110
	v_and_b32_e32 v117, 0xffff0000, v110
	v_lshlrev_b32_e32 v110, 16, v111
	v_and_b32_e32 v111, 0xffff0000, v111
	v_lshl_add_u64 v[82:83], v[82:83], 0, v[152:153]
	v_lshlrev_b32_e32 v118, 16, v112
	v_and_b32_e32 v119, 0xffff0000, v112
	v_lshlrev_b32_e32 v112, 16, v113
	v_and_b32_e32 v113, 0xffff0000, v113
	s_nop 0
	v_pk_add_f32 v[80:81], v[80:81], v[206:207]
	v_pk_add_f32 v[78:79], v[78:79], v[204:205]
	v_pk_add_f32 v[76:77], v[76:77], v[210:211]
	v_pk_add_f32 v[74:75], v[74:75], v[208:209]
	v_mul_f32_e32 v78, 0xbfb8aa3b, v78
	v_mul_f32_e32 v79, 0xbfb8aa3b, v79
	v_mul_f32_e32 v80, 0xbfb8aa3b, v80
	v_mul_f32_e32 v81, 0xbfb8aa3b, v81
	v_mul_f32_e32 v74, 0xbfb8aa3b, v74
	v_mul_f32_e32 v75, 0xbfb8aa3b, v75
	v_mul_f32_e32 v76, 0xbfb8aa3b, v76
	v_mul_f32_e32 v77, 0xbfb8aa3b, v77
	v_exp_f32_e32 v78, v78
	v_exp_f32_e32 v79, v79
	v_exp_f32_e32 v80, v80
	v_exp_f32_e32 v81, v81
	v_exp_f32_e32 v74, v74
	v_exp_f32_e32 v75, v75
	v_exp_f32_e32 v76, v76
	v_exp_f32_e32 v77, v77
	v_add_f32_e32 v78, 1.0, v78
	v_add_f32_e32 v79, 1.0, v79
	v_add_f32_e32 v80, 1.0, v80
	v_add_f32_e32 v81, 1.0, v81
	v_add_f32_e32 v84, 1.0, v74
	v_add_f32_e32 v85, 1.0, v75
	v_add_f32_e32 v86, 1.0, v76
	v_add_f32_e32 v87, 1.0, v77
	v_rcp_f32_e32 v74, v78
	v_rcp_f32_e32 v75, v79
	v_rcp_f32_e32 v76, v80
	v_rcp_f32_e32 v77, v81
	v_rcp_f32_e32 v78, v84
	v_rcp_f32_e32 v80, v86
	v_rcp_f32_e32 v81, v87
	v_rcp_f32_e32 v79, v85
	v_pk_mul_f32 v[76:77], v[76:77], v[94:95]
	v_pk_mul_f32 v[74:75], v[74:75], v[92:93]
	v_pk_mul_f32 v[80:81], v[80:81], v[114:115]
	v_pk_mul_f32 v[78:79], v[78:79], v[96:97]
	v_pk_mul_f32 v[76:77], v[76:77], v[110:111]
	v_pk_mul_f32 v[74:75], v[74:75], v[116:117]
	v_pk_mul_f32 v[80:81], v[80:81], v[112:113]
	v_pk_mul_f32 v[78:79], v[78:79], v[118:119]
	v_cvt_pk_bf16_f32 v74, v74, v75
	v_cvt_pk_bf16_f32 v75, v76, v77
	v_add_u32_e32 v88, 0x80, v154
	v_cvt_pk_bf16_f32 v76, v78, v79
	v_cvt_pk_bf16_f32 v77, v80, v81
	global_store_dwordx4 v[82:83], v[74:77], off
	s_nop 0
	s_nop 0
	s_nop 0
	v_ashrrev_i32_e32 v89, 31, v88
	v_lshlrev_b64 v[96:97], 11, v[88:89]
	v_lshl_add_u64 v[84:85], s[10:11], 0, v[96:97]
	v_lshl_add_u64 v[110:111], v[84:85], 0, v[152:153]
	v_lshlrev_b32_e32 v84, 16, v106
	v_and_b32_e32 v85, 0xffff0000, v106
	v_lshlrev_b32_e32 v86, 16, v107
	v_and_b32_e32 v87, 0xffff0000, v107
	v_lshlrev_b32_e32 v94, 16, v102
	v_and_b32_e32 v95, 0xffff0000, v102
	v_lshlrev_b32_e32 v90, 16, v108
	v_and_b32_e32 v91, 0xffff0000, v108
	v_lshlrev_b32_e32 v92, 16, v109
	v_and_b32_e32 v93, 0xffff0000, v109
	v_lshlrev_b32_e32 v102, 16, v103
	v_and_b32_e32 v103, 0xffff0000, v103
	v_lshlrev_b32_e32 v106, 16, v104
	v_and_b32_e32 v107, 0xffff0000, v104
	v_lshlrev_b32_e32 v104, 16, v105
	v_and_b32_e32 v105, 0xffff0000, v105
	s_nop 0
	v_pk_add_f32 v[70:71], v[70:71], v[212:213]
	v_pk_add_f32 v[72:73], v[72:73], v[214:215]
	v_pk_add_f32 v[66:67], v[66:67], v[216:217]
	v_mul_f32_e32 v70, 0xbfb8aa3b, v70
	v_mul_f32_e32 v71, 0xbfb8aa3b, v71
	v_pk_add_f32 v[68:69], v[68:69], v[218:219]
	v_mul_f32_e32 v72, 0xbfb8aa3b, v72
	v_mul_f32_e32 v73, 0xbfb8aa3b, v73
	v_mul_f32_e32 v66, 0xbfb8aa3b, v66
	v_mul_f32_e32 v67, 0xbfb8aa3b, v67
	v_exp_f32_e32 v70, v70
	v_exp_f32_e32 v71, v71
	v_mul_f32_e32 v68, 0xbfb8aa3b, v68
	v_mul_f32_e32 v69, 0xbfb8aa3b, v69
	v_exp_f32_e32 v72, v72
	v_exp_f32_e32 v73, v73
	v_exp_f32_e32 v66, v66
	v_exp_f32_e32 v67, v67
	v_exp_f32_e32 v68, v68
	v_exp_f32_e32 v69, v69
	v_add_f32_e32 v70, 1.0, v70
	v_add_f32_e32 v71, 1.0, v71
	v_add_f32_e32 v72, 1.0, v72
	v_add_f32_e32 v73, 1.0, v73
	v_add_f32_e32 v74, 1.0, v66
	v_add_f32_e32 v75, 1.0, v67
	v_rcp_f32_e32 v66, v70
	v_rcp_f32_e32 v67, v71
	v_add_f32_e32 v76, 1.0, v68
	v_add_f32_e32 v77, 1.0, v69
	v_rcp_f32_e32 v68, v72
	v_rcp_f32_e32 v69, v73
	v_rcp_f32_e32 v70, v74
	v_rcp_f32_e32 v72, v76
	v_rcp_f32_e32 v73, v77
	v_rcp_f32_e32 v71, v75
	v_pk_mul_f32 v[66:67], v[66:67], v[84:85]
	v_pk_mul_f32 v[68:69], v[68:69], v[86:87]
	v_pk_mul_f32 v[66:67], v[66:67], v[94:95]
	v_pk_mul_f32 v[72:73], v[72:73], v[92:93]
	v_pk_mul_f32 v[70:71], v[70:71], v[90:91]
	v_pk_mul_f32 v[68:69], v[68:69], v[102:103]
	v_cvt_pk_bf16_f32 v66, v66, v67
	v_pk_mul_f32 v[72:73], v[72:73], v[104:105]
	v_cvt_pk_bf16_f32 v67, v68, v69
	v_pk_mul_f32 v[70:71], v[70:71], v[106:107]
	s_nop 0
	v_cvt_pk_bf16_f32 v68, v70, v71
	v_cvt_pk_bf16_f32 v69, v72, v73
	global_store_dwordx4 v[82:83], v[66:69], off offset:256
	global_load_dwordx4 v[84:87], v[110:111], off
	v_lshl_add_u64 v[72:73], s[14:15], 0, v[96:97]
	v_mad_i64_i32 v[66:67], s[0:1], v88, s16, v[156:157]
	v_lshl_add_u64 v[66:67], v[66:67], 0, v[152:153]
	global_load_dwordx4 v[88:91], v[66:67], off offset:2048
	s_nop 0
	s_nop 0
	v_add_u32_e32 v68, 0x90, v154
	v_ashrrev_i32_e32 v69, 31, v68
	v_lshlrev_b64 v[82:83], 11, v[68:69]
	v_mad_i64_i32 v[70:71], s[0:1], v68, s16, v[156:157]
	v_lshl_add_u64 v[68:69], s[10:11], 0, v[82:83]
	v_lshl_add_u64 v[68:69], v[68:69], 0, v[152:153]
	v_lshl_add_u64 v[96:97], v[70:71], 0, v[152:153]
	v_lshl_add_u64 v[114:115], v[72:73], 0, v[152:153]
	global_load_dwordx4 v[106:109], v[110:111], off offset:256
	s_nop 0
	global_load_dwordx4 v[110:113], v[66:67], off offset:2304
	global_load_dwordx4 v[78:81], v[68:69], off
	global_load_dwordx4 v[70:73], v[68:69], off offset:256
	global_load_dwordx4 v[74:77], v[96:97], off offset:2048
	s_nop 0
	global_load_dwordx4 v[66:69], v[96:97], off offset:2304
	s_waitcnt vmcnt(0)
	v_lshlrev_b32_e32 v96, 16, v84
	v_and_b32_e32 v97, 0xffff0000, v84
	v_lshlrev_b32_e32 v84, 16, v85
	v_and_b32_e32 v85, 0xffff0000, v85
	s_waitcnt lgkmcnt(0)
	v_pk_add_f32 v[64:65], v[64:65], v[206:207]
	v_pk_add_f32 v[62:63], v[62:63], v[204:205]
	v_pk_add_f32 v[60:61], v[60:61], v[210:211]
	v_pk_add_f32 v[58:59], v[58:59], v[208:209]
	v_mul_f32_e32 v62, 0xbfb8aa3b, v62
	v_mul_f32_e32 v63, 0xbfb8aa3b, v63
	v_mul_f32_e32 v64, 0xbfb8aa3b, v64
	v_mul_f32_e32 v65, 0xbfb8aa3b, v65
	v_mul_f32_e32 v58, 0xbfb8aa3b, v58
	v_mul_f32_e32 v59, 0xbfb8aa3b, v59
	v_mul_f32_e32 v60, 0xbfb8aa3b, v60
	v_mul_f32_e32 v61, 0xbfb8aa3b, v61
	v_exp_f32_e32 v62, v62
	v_exp_f32_e32 v63, v63
	v_exp_f32_e32 v64, v64
	v_exp_f32_e32 v65, v65
	v_exp_f32_e32 v58, v58
	v_exp_f32_e32 v59, v59
	v_exp_f32_e32 v60, v60
	v_exp_f32_e32 v61, v61
	v_add_f32_e32 v62, 1.0, v62
	v_add_f32_e32 v63, 1.0, v63
	v_add_f32_e32 v64, 1.0, v64
	v_add_f32_e32 v65, 1.0, v65
	v_add_f32_e32 v92, 1.0, v58
	v_add_f32_e32 v93, 1.0, v59
	v_add_f32_e32 v94, 1.0, v60
	v_add_f32_e32 v95, 1.0, v61
	v_rcp_f32_e32 v58, v62
	v_rcp_f32_e32 v59, v63
	v_rcp_f32_e32 v60, v64
	v_rcp_f32_e32 v61, v65
	v_rcp_f32_e32 v62, v92
	v_rcp_f32_e32 v64, v94
	v_rcp_f32_e32 v65, v95
	v_rcp_f32_e32 v63, v93
	v_lshlrev_b32_e32 v116, 16, v86
	v_and_b32_e32 v117, 0xffff0000, v86
	v_lshlrev_b32_e32 v86, 16, v87
	v_and_b32_e32 v87, 0xffff0000, v87
	v_lshlrev_b32_e32 v118, 16, v88
	v_and_b32_e32 v119, 0xffff0000, v88
	v_lshlrev_b32_e32 v88, 16, v89
	v_and_b32_e32 v89, 0xffff0000, v89
	v_pk_mul_f32 v[60:61], v[60:61], v[84:85]
	v_pk_mul_f32 v[58:59], v[58:59], v[96:97]
	v_lshlrev_b32_e32 v120, 16, v90
	v_and_b32_e32 v121, 0xffff0000, v90
	v_lshlrev_b32_e32 v90, 16, v91
	v_and_b32_e32 v91, 0xffff0000, v91
	v_pk_mul_f32 v[64:65], v[64:65], v[86:87]
	v_pk_mul_f32 v[62:63], v[62:63], v[116:117]
	v_pk_mul_f32 v[60:61], v[60:61], v[88:89]
	v_pk_mul_f32 v[58:59], v[58:59], v[118:119]
	v_pk_mul_f32 v[64:65], v[64:65], v[90:91]
	v_pk_mul_f32 v[62:63], v[62:63], v[120:121]
	v_cvt_pk_bf16_f32 v58, v58, v59
	v_cvt_pk_bf16_f32 v59, v60, v61
	v_lshlrev_b32_e32 v84, 16, v106
	v_cvt_pk_bf16_f32 v60, v62, v63
	v_cvt_pk_bf16_f32 v61, v64, v65
	global_store_dwordx4 v[114:115], v[58:61], off
	s_nop 0
	s_nop 0
	s_nop 0
	v_and_b32_e32 v85, 0xffff0000, v106
	v_lshlrev_b32_e32 v86, 16, v107
	v_and_b32_e32 v87, 0xffff0000, v107
	v_lshlrev_b32_e32 v88, 16, v108
	v_and_b32_e32 v89, 0xffff0000, v108
	v_lshlrev_b32_e32 v90, 16, v109
	v_and_b32_e32 v91, 0xffff0000, v109
	v_lshlrev_b32_e32 v92, 16, v110
	v_and_b32_e32 v93, 0xffff0000, v110
	v_lshlrev_b32_e32 v94, 16, v111
	v_and_b32_e32 v95, 0xffff0000, v111
	v_lshlrev_b32_e32 v96, 16, v112
	v_and_b32_e32 v97, 0xffff0000, v112
	v_lshlrev_b32_e32 v102, 16, v113
	v_and_b32_e32 v103, 0xffff0000, v113
	s_nop 0
	v_pk_add_f32 v[56:57], v[56:57], v[214:215]
	v_pk_add_f32 v[54:55], v[54:55], v[212:213]
	v_pk_add_f32 v[52:53], v[52:53], v[218:219]
	v_pk_add_f32 v[50:51], v[50:51], v[216:217]
	v_mul_f32_e32 v54, 0xbfb8aa3b, v54
	v_mul_f32_e32 v55, 0xbfb8aa3b, v55
	v_mul_f32_e32 v56, 0xbfb8aa3b, v56
	v_mul_f32_e32 v57, 0xbfb8aa3b, v57
	v_mul_f32_e32 v50, 0xbfb8aa3b, v50
	v_mul_f32_e32 v51, 0xbfb8aa3b, v51
	v_mul_f32_e32 v52, 0xbfb8aa3b, v52
	v_mul_f32_e32 v53, 0xbfb8aa3b, v53
	v_exp_f32_e32 v54, v54
	v_exp_f32_e32 v55, v55
	v_exp_f32_e32 v56, v56
	v_exp_f32_e32 v57, v57
	v_exp_f32_e32 v50, v50
	v_exp_f32_e32 v51, v51
	v_exp_f32_e32 v52, v52
	v_exp_f32_e32 v53, v53
	v_add_f32_e32 v54, 1.0, v54
	v_add_f32_e32 v55, 1.0, v55
	v_add_f32_e32 v56, 1.0, v56
	v_add_f32_e32 v57, 1.0, v57
	v_add_f32_e32 v58, 1.0, v50
	v_add_f32_e32 v59, 1.0, v51
	v_add_f32_e32 v60, 1.0, v52
	v_add_f32_e32 v61, 1.0, v53
	v_rcp_f32_e32 v50, v54
	v_rcp_f32_e32 v51, v55
	v_rcp_f32_e32 v52, v56
	v_rcp_f32_e32 v53, v57
	v_rcp_f32_e32 v54, v58
	v_rcp_f32_e32 v56, v60
	v_rcp_f32_e32 v57, v61
	v_rcp_f32_e32 v55, v59
	v_pk_mul_f32 v[52:53], v[52:53], v[86:87]
	v_pk_mul_f32 v[50:51], v[50:51], v[84:85]
	v_pk_mul_f32 v[56:57], v[56:57], v[90:91]
	v_pk_mul_f32 v[54:55], v[54:55], v[88:89]
	v_pk_mul_f32 v[52:53], v[52:53], v[94:95]
	v_pk_mul_f32 v[50:51], v[50:51], v[92:93]
	v_pk_mul_f32 v[56:57], v[56:57], v[102:103]
	v_pk_mul_f32 v[54:55], v[54:55], v[96:97]
	v_cvt_pk_bf16_f32 v50, v50, v51
	v_cvt_pk_bf16_f32 v51, v52, v53
	v_lshlrev_b32_e32 v60, 16, v78
	v_cvt_pk_bf16_f32 v52, v54, v55
	v_cvt_pk_bf16_f32 v53, v56, v57
	global_store_dwordx4 v[114:115], v[50:53], off offset:256
	s_nop 0
	s_nop 0
	s_nop 0
	v_and_b32_e32 v61, 0xffff0000, v78
	v_lshlrev_b32_e32 v62, 16, v79
	v_and_b32_e32 v63, 0xffff0000, v79
	v_lshl_add_u64 v[50:51], s[14:15], 0, v[82:83]
	v_lshlrev_b32_e32 v64, 16, v80
	v_and_b32_e32 v65, 0xffff0000, v80
	v_lshlrev_b32_e32 v78, 16, v81
	v_and_b32_e32 v79, 0xffff0000, v81
	v_lshlrev_b32_e32 v80, 16, v74
	v_and_b32_e32 v81, 0xffff0000, v74
	v_lshlrev_b32_e32 v74, 16, v75
	v_and_b32_e32 v75, 0xffff0000, v75
	v_lshl_add_u64 v[50:51], v[50:51], 0, v[152:153]
	v_lshlrev_b32_e32 v82, 16, v76
	v_and_b32_e32 v83, 0xffff0000, v76
	v_lshlrev_b32_e32 v76, 16, v77
	v_and_b32_e32 v77, 0xffff0000, v77
	s_nop 0
	v_pk_add_f32 v[48:49], v[48:49], v[206:207]
	v_pk_add_f32 v[46:47], v[46:47], v[204:205]
	v_pk_add_f32 v[44:45], v[44:45], v[210:211]
	v_pk_add_f32 v[42:43], v[42:43], v[208:209]
	v_mul_f32_e32 v46, 0xbfb8aa3b, v46
	v_mul_f32_e32 v47, 0xbfb8aa3b, v47
	v_mul_f32_e32 v48, 0xbfb8aa3b, v48
	v_mul_f32_e32 v49, 0xbfb8aa3b, v49
	v_mul_f32_e32 v42, 0xbfb8aa3b, v42
	v_mul_f32_e32 v43, 0xbfb8aa3b, v43
	v_mul_f32_e32 v44, 0xbfb8aa3b, v44
	v_mul_f32_e32 v45, 0xbfb8aa3b, v45
	v_exp_f32_e32 v46, v46
	v_exp_f32_e32 v47, v47
	v_exp_f32_e32 v48, v48
	v_exp_f32_e32 v49, v49
	v_exp_f32_e32 v42, v42
	v_exp_f32_e32 v43, v43
	v_exp_f32_e32 v44, v44
	v_exp_f32_e32 v45, v45
	v_add_f32_e32 v46, 1.0, v46
	v_add_f32_e32 v47, 1.0, v47
	v_add_f32_e32 v48, 1.0, v48
	v_add_f32_e32 v49, 1.0, v49
	v_add_f32_e32 v52, 1.0, v42
	v_add_f32_e32 v53, 1.0, v43
	v_add_f32_e32 v54, 1.0, v44
	v_add_f32_e32 v55, 1.0, v45
	v_rcp_f32_e32 v42, v46
	v_rcp_f32_e32 v43, v47
	v_rcp_f32_e32 v44, v48
	v_rcp_f32_e32 v45, v49
	v_rcp_f32_e32 v46, v52
	v_rcp_f32_e32 v48, v54
	v_rcp_f32_e32 v49, v55
	v_rcp_f32_e32 v47, v53
	v_pk_mul_f32 v[44:45], v[44:45], v[62:63]
	v_pk_mul_f32 v[42:43], v[42:43], v[60:61]
	v_pk_mul_f32 v[48:49], v[48:49], v[78:79]
	v_pk_mul_f32 v[46:47], v[46:47], v[64:65]
	v_pk_mul_f32 v[44:45], v[44:45], v[74:75]
	v_pk_mul_f32 v[42:43], v[42:43], v[80:81]
	v_pk_mul_f32 v[48:49], v[48:49], v[76:77]
	v_pk_mul_f32 v[46:47], v[46:47], v[82:83]
	v_cvt_pk_bf16_f32 v42, v42, v43
	v_cvt_pk_bf16_f32 v43, v44, v45
	v_add_u32_e32 v56, 0xa0, v154
	v_cvt_pk_bf16_f32 v44, v46, v47
	v_cvt_pk_bf16_f32 v45, v48, v49
	global_store_dwordx4 v[50:51], v[42:45], off
	s_nop 0
	s_nop 0
	s_nop 0
	v_ashrrev_i32_e32 v57, 31, v56
	v_lshlrev_b64 v[74:75], 11, v[56:57]
	v_lshl_add_u64 v[52:53], s[10:11], 0, v[74:75]
	v_lshl_add_u64 v[76:77], v[52:53], 0, v[152:153]
	v_lshlrev_b32_e32 v52, 16, v70
	v_and_b32_e32 v53, 0xffff0000, v70
	v_lshlrev_b32_e32 v54, 16, v71
	v_and_b32_e32 v55, 0xffff0000, v71
	v_lshlrev_b32_e32 v62, 16, v66
	v_and_b32_e32 v63, 0xffff0000, v66
	v_lshlrev_b32_e32 v58, 16, v72
	v_and_b32_e32 v59, 0xffff0000, v72
	v_lshlrev_b32_e32 v60, 16, v73
	v_and_b32_e32 v61, 0xffff0000, v73
	v_lshlrev_b32_e32 v64, 16, v67
	v_and_b32_e32 v65, 0xffff0000, v67
	v_lshlrev_b32_e32 v66, 16, v68
	v_and_b32_e32 v67, 0xffff0000, v68
	v_lshlrev_b32_e32 v68, 16, v69
	v_and_b32_e32 v69, 0xffff0000, v69
	s_nop 0
	v_pk_add_f32 v[38:39], v[38:39], v[212:213]
	v_pk_add_f32 v[40:41], v[40:41], v[214:215]
	v_pk_add_f32 v[34:35], v[34:35], v[216:217]
	v_mul_f32_e32 v38, 0xbfb8aa3b, v38
	v_mul_f32_e32 v39, 0xbfb8aa3b, v39
	v_pk_add_f32 v[36:37], v[36:37], v[218:219]
	v_mul_f32_e32 v40, 0xbfb8aa3b, v40
	v_mul_f32_e32 v41, 0xbfb8aa3b, v41
	v_mul_f32_e32 v34, 0xbfb8aa3b, v34
	v_mul_f32_e32 v35, 0xbfb8aa3b, v35
	v_exp_f32_e32 v38, v38
	v_exp_f32_e32 v39, v39
	v_mul_f32_e32 v36, 0xbfb8aa3b, v36
	v_mul_f32_e32 v37, 0xbfb8aa3b, v37
	v_exp_f32_e32 v40, v40
	v_exp_f32_e32 v41, v41
	v_exp_f32_e32 v34, v34
	v_exp_f32_e32 v35, v35
	v_exp_f32_e32 v36, v36
	v_exp_f32_e32 v37, v37
	v_add_f32_e32 v38, 1.0, v38
	v_add_f32_e32 v39, 1.0, v39
	v_add_f32_e32 v40, 1.0, v40
	v_add_f32_e32 v41, 1.0, v41
	v_add_f32_e32 v42, 1.0, v34
	v_add_f32_e32 v43, 1.0, v35
	v_rcp_f32_e32 v34, v38
	v_rcp_f32_e32 v35, v39
	v_add_f32_e32 v44, 1.0, v36
	v_add_f32_e32 v45, 1.0, v37
	v_rcp_f32_e32 v36, v40
	v_rcp_f32_e32 v37, v41
	v_rcp_f32_e32 v38, v42
	v_rcp_f32_e32 v40, v44
	v_rcp_f32_e32 v41, v45
	v_rcp_f32_e32 v39, v43
	v_pk_mul_f32 v[34:35], v[34:35], v[52:53]
	v_pk_mul_f32 v[36:37], v[36:37], v[54:55]
	v_pk_mul_f32 v[34:35], v[34:35], v[62:63]
	v_pk_mul_f32 v[40:41], v[40:41], v[60:61]
	v_pk_mul_f32 v[38:39], v[38:39], v[58:59]
	v_pk_mul_f32 v[36:37], v[36:37], v[64:65]
	v_cvt_pk_bf16_f32 v34, v34, v35
	v_pk_mul_f32 v[40:41], v[40:41], v[68:69]
	v_cvt_pk_bf16_f32 v35, v36, v37
	v_pk_mul_f32 v[38:39], v[38:39], v[66:67]
	s_nop 0
	v_cvt_pk_bf16_f32 v36, v38, v39
	v_cvt_pk_bf16_f32 v37, v40, v41
	global_store_dwordx4 v[50:51], v[34:37], off offset:256
	global_load_dwordx4 v[52:55], v[76:77], off
	v_lshl_add_u64 v[40:41], s[14:15], 0, v[74:75]
	v_mad_i64_i32 v[34:35], s[0:1], v56, s16, v[156:157]
	v_lshl_add_u64 v[34:35], v[34:35], 0, v[152:153]
	global_load_dwordx4 v[56:59], v[34:35], off offset:2048
	s_nop 0
	s_nop 0
	v_add_u32_e32 v36, 0xb0, v154
	v_ashrrev_i32_e32 v37, 31, v36
	v_lshlrev_b64 v[50:51], 11, v[36:37]
	v_mad_i64_i32 v[38:39], s[0:1], v36, s16, v[156:157]
	v_lshl_add_u64 v[36:37], s[10:11], 0, v[50:51]
	v_lshl_add_u64 v[36:37], v[36:37], 0, v[152:153]
	v_lshl_add_u64 v[78:79], v[38:39], 0, v[152:153]
	v_lshl_add_u64 v[80:81], v[40:41], 0, v[152:153]
	global_load_dwordx4 v[68:71], v[76:77], off offset:256
	global_load_dwordx4 v[72:75], v[34:35], off offset:2304
	global_load_dwordx4 v[46:49], v[36:37], off
	global_load_dwordx4 v[38:41], v[36:37], off offset:256
	global_load_dwordx4 v[42:45], v[78:79], off offset:2048
	s_nop 0
	global_load_dwordx4 v[34:37], v[78:79], off offset:2304
	s_waitcnt vmcnt(0)
	v_lshlrev_b32_e32 v76, 16, v52
	v_and_b32_e32 v77, 0xffff0000, v52
	v_lshlrev_b32_e32 v52, 16, v53
	v_and_b32_e32 v53, 0xffff0000, v53
	s_waitcnt lgkmcnt(0)
	v_pk_add_f32 v[32:33], v[32:33], v[206:207]
	v_pk_add_f32 v[30:31], v[30:31], v[204:205]
	v_pk_add_f32 v[28:29], v[28:29], v[210:211]
	v_pk_add_f32 v[26:27], v[26:27], v[208:209]
	v_mul_f32_e32 v30, 0xbfb8aa3b, v30
	v_mul_f32_e32 v31, 0xbfb8aa3b, v31
	v_mul_f32_e32 v32, 0xbfb8aa3b, v32
	v_mul_f32_e32 v33, 0xbfb8aa3b, v33
	v_mul_f32_e32 v26, 0xbfb8aa3b, v26
	v_mul_f32_e32 v27, 0xbfb8aa3b, v27
	v_mul_f32_e32 v28, 0xbfb8aa3b, v28
	v_mul_f32_e32 v29, 0xbfb8aa3b, v29
	v_exp_f32_e32 v30, v30
	v_exp_f32_e32 v31, v31
	v_exp_f32_e32 v32, v32
	v_exp_f32_e32 v33, v33
	v_exp_f32_e32 v26, v26
	v_exp_f32_e32 v27, v27
	v_exp_f32_e32 v28, v28
	v_exp_f32_e32 v29, v29
	v_add_f32_e32 v30, 1.0, v30
	v_add_f32_e32 v31, 1.0, v31
	v_add_f32_e32 v32, 1.0, v32
	v_add_f32_e32 v33, 1.0, v33
	v_add_f32_e32 v60, 1.0, v26
	v_add_f32_e32 v61, 1.0, v27
	v_add_f32_e32 v62, 1.0, v28
	v_add_f32_e32 v63, 1.0, v29
	v_rcp_f32_e32 v26, v30
	v_rcp_f32_e32 v27, v31
	v_rcp_f32_e32 v28, v32
	v_rcp_f32_e32 v29, v33
	v_rcp_f32_e32 v30, v60
	v_rcp_f32_e32 v32, v62
	v_rcp_f32_e32 v33, v63
	v_rcp_f32_e32 v31, v61
	v_lshlrev_b32_e32 v78, 16, v54
	v_and_b32_e32 v79, 0xffff0000, v54
	v_lshlrev_b32_e32 v54, 16, v55
	v_and_b32_e32 v55, 0xffff0000, v55
	v_lshlrev_b32_e32 v82, 16, v56
	v_and_b32_e32 v83, 0xffff0000, v56
	v_lshlrev_b32_e32 v56, 16, v57
	v_and_b32_e32 v57, 0xffff0000, v57
	v_pk_mul_f32 v[28:29], v[28:29], v[52:53]
	v_pk_mul_f32 v[26:27], v[26:27], v[76:77]
	v_lshlrev_b32_e32 v84, 16, v58
	v_and_b32_e32 v85, 0xffff0000, v58
	v_lshlrev_b32_e32 v58, 16, v59
	v_and_b32_e32 v59, 0xffff0000, v59
	v_pk_mul_f32 v[32:33], v[32:33], v[54:55]
	v_pk_mul_f32 v[30:31], v[30:31], v[78:79]
	v_pk_mul_f32 v[28:29], v[28:29], v[56:57]
	v_pk_mul_f32 v[26:27], v[26:27], v[82:83]
	v_pk_mul_f32 v[32:33], v[32:33], v[58:59]
	v_pk_mul_f32 v[30:31], v[30:31], v[84:85]
	v_cvt_pk_bf16_f32 v26, v26, v27
	v_cvt_pk_bf16_f32 v27, v28, v29
	v_lshlrev_b32_e32 v52, 16, v68
	v_cvt_pk_bf16_f32 v28, v30, v31
	v_cvt_pk_bf16_f32 v29, v32, v33
	global_store_dwordx4 v[80:81], v[26:29], off
	s_nop 0
	s_nop 0
	s_nop 0
	v_and_b32_e32 v53, 0xffff0000, v68
	v_lshlrev_b32_e32 v54, 16, v69
	v_and_b32_e32 v55, 0xffff0000, v69
	v_lshlrev_b32_e32 v56, 16, v70
	v_and_b32_e32 v57, 0xffff0000, v70
	v_lshlrev_b32_e32 v58, 16, v71
	v_and_b32_e32 v59, 0xffff0000, v71
	v_lshlrev_b32_e32 v60, 16, v72
	v_and_b32_e32 v61, 0xffff0000, v72
	v_lshlrev_b32_e32 v62, 16, v73
	v_and_b32_e32 v63, 0xffff0000, v73
	v_lshlrev_b32_e32 v64, 16, v74
	v_and_b32_e32 v65, 0xffff0000, v74
	v_lshlrev_b32_e32 v66, 16, v75
	v_and_b32_e32 v67, 0xffff0000, v75
	s_nop 0
	v_pk_add_f32 v[24:25], v[24:25], v[214:215]
	v_pk_add_f32 v[22:23], v[22:23], v[212:213]
	v_pk_add_f32 v[20:21], v[20:21], v[218:219]
	v_pk_add_f32 v[18:19], v[18:19], v[216:217]
	v_mul_f32_e32 v22, 0xbfb8aa3b, v22
	v_mul_f32_e32 v23, 0xbfb8aa3b, v23
	v_mul_f32_e32 v24, 0xbfb8aa3b, v24
	v_mul_f32_e32 v25, 0xbfb8aa3b, v25
	v_mul_f32_e32 v18, 0xbfb8aa3b, v18
	v_mul_f32_e32 v19, 0xbfb8aa3b, v19
	v_mul_f32_e32 v20, 0xbfb8aa3b, v20
	v_mul_f32_e32 v21, 0xbfb8aa3b, v21
	v_exp_f32_e32 v22, v22
	v_exp_f32_e32 v23, v23
	v_exp_f32_e32 v24, v24
	v_exp_f32_e32 v25, v25
	v_exp_f32_e32 v18, v18
	v_exp_f32_e32 v19, v19
	v_exp_f32_e32 v20, v20
	v_exp_f32_e32 v21, v21
	v_add_f32_e32 v22, 1.0, v22
	v_add_f32_e32 v23, 1.0, v23
	v_add_f32_e32 v24, 1.0, v24
	v_add_f32_e32 v25, 1.0, v25
	v_add_f32_e32 v26, 1.0, v18
	v_add_f32_e32 v27, 1.0, v19
	v_add_f32_e32 v28, 1.0, v20
	v_add_f32_e32 v29, 1.0, v21
	v_rcp_f32_e32 v18, v22
	v_rcp_f32_e32 v19, v23
	v_rcp_f32_e32 v20, v24
	v_rcp_f32_e32 v21, v25
	v_rcp_f32_e32 v22, v26
	v_rcp_f32_e32 v24, v28
	v_rcp_f32_e32 v25, v29
	v_rcp_f32_e32 v23, v27
	v_pk_mul_f32 v[20:21], v[20:21], v[54:55]
	v_pk_mul_f32 v[18:19], v[18:19], v[52:53]
	v_pk_mul_f32 v[24:25], v[24:25], v[58:59]
	v_pk_mul_f32 v[22:23], v[22:23], v[56:57]
	v_pk_mul_f32 v[20:21], v[20:21], v[62:63]
	v_pk_mul_f32 v[18:19], v[18:19], v[60:61]
	v_pk_mul_f32 v[24:25], v[24:25], v[66:67]
	v_pk_mul_f32 v[22:23], v[22:23], v[64:65]
	v_cvt_pk_bf16_f32 v18, v18, v19
	v_cvt_pk_bf16_f32 v19, v20, v21
	v_lshlrev_b32_e32 v28, 16, v46
	v_cvt_pk_bf16_f32 v20, v22, v23
	v_cvt_pk_bf16_f32 v21, v24, v25
	global_store_dwordx4 v[80:81], v[18:21], off offset:256
	s_nop 0
	s_nop 0
	s_nop 0
	v_and_b32_e32 v29, 0xffff0000, v46
	v_lshlrev_b32_e32 v30, 16, v47
	v_and_b32_e32 v31, 0xffff0000, v47
	v_lshl_add_u64 v[26:27], s[14:15], 0, v[50:51]
	v_lshlrev_b32_e32 v32, 16, v48
	v_and_b32_e32 v33, 0xffff0000, v48
	v_lshlrev_b32_e32 v46, 16, v49
	v_and_b32_e32 v47, 0xffff0000, v49
	v_lshlrev_b32_e32 v48, 16, v42
	v_and_b32_e32 v49, 0xffff0000, v42
	v_lshlrev_b32_e32 v42, 16, v43
	v_and_b32_e32 v43, 0xffff0000, v43
	v_lshl_add_u64 v[26:27], v[26:27], 0, v[152:153]
	v_lshlrev_b32_e32 v50, 16, v44
	v_and_b32_e32 v51, 0xffff0000, v44
	v_lshlrev_b32_e32 v44, 16, v45
	v_and_b32_e32 v45, 0xffff0000, v45
	s_nop 0
	v_pk_add_f32 v[16:17], v[16:17], v[206:207]
	v_pk_add_f32 v[14:15], v[14:15], v[204:205]
	v_pk_add_f32 v[12:13], v[12:13], v[210:211]
	v_pk_add_f32 v[10:11], v[10:11], v[208:209]
	v_mul_f32_e32 v14, 0xbfb8aa3b, v14
	v_mul_f32_e32 v15, 0xbfb8aa3b, v15
	v_mul_f32_e32 v16, 0xbfb8aa3b, v16
	v_mul_f32_e32 v17, 0xbfb8aa3b, v17
	v_mul_f32_e32 v10, 0xbfb8aa3b, v10
	v_mul_f32_e32 v11, 0xbfb8aa3b, v11
	v_mul_f32_e32 v12, 0xbfb8aa3b, v12
	v_mul_f32_e32 v13, 0xbfb8aa3b, v13
	v_exp_f32_e32 v14, v14
	v_exp_f32_e32 v15, v15
	v_exp_f32_e32 v16, v16
	v_exp_f32_e32 v17, v17
	v_exp_f32_e32 v10, v10
	v_exp_f32_e32 v11, v11
	v_exp_f32_e32 v12, v12
	v_exp_f32_e32 v13, v13
	v_add_f32_e32 v14, 1.0, v14
	v_add_f32_e32 v15, 1.0, v15
	v_add_f32_e32 v16, 1.0, v16
	v_add_f32_e32 v17, 1.0, v17
	v_add_f32_e32 v18, 1.0, v10
	v_add_f32_e32 v19, 1.0, v11
	v_add_f32_e32 v20, 1.0, v12
	v_add_f32_e32 v21, 1.0, v13
	v_rcp_f32_e32 v10, v14
	v_rcp_f32_e32 v11, v15
	v_rcp_f32_e32 v12, v16
	v_rcp_f32_e32 v13, v17
	v_rcp_f32_e32 v14, v18
	v_rcp_f32_e32 v16, v20
	v_rcp_f32_e32 v17, v21
	v_rcp_f32_e32 v15, v19
	v_pk_mul_f32 v[12:13], v[12:13], v[30:31]
	v_pk_mul_f32 v[10:11], v[10:11], v[28:29]
	v_pk_mul_f32 v[16:17], v[16:17], v[46:47]
	v_pk_mul_f32 v[14:15], v[14:15], v[32:33]
	v_pk_mul_f32 v[12:13], v[12:13], v[42:43]
	v_pk_mul_f32 v[10:11], v[10:11], v[48:49]
	v_pk_mul_f32 v[16:17], v[16:17], v[44:45]
	v_pk_mul_f32 v[14:15], v[14:15], v[50:51]
	v_cvt_pk_bf16_f32 v10, v10, v11
	v_cvt_pk_bf16_f32 v11, v12, v13
	v_lshlrev_b32_e32 v18, 16, v38
	v_cvt_pk_bf16_f32 v12, v14, v15
	v_cvt_pk_bf16_f32 v13, v16, v17
	global_store_dwordx4 v[26:27], v[10:13], off
	s_nop 0
	s_nop 0
	s_nop 0
	v_and_b32_e32 v19, 0xffff0000, v38
	v_lshlrev_b32_e32 v20, 16, v39
	v_and_b32_e32 v21, 0xffff0000, v39
	v_lshlrev_b32_e32 v22, 16, v40
	v_and_b32_e32 v23, 0xffff0000, v40
	v_lshlrev_b32_e32 v24, 16, v41
	v_and_b32_e32 v25, 0xffff0000, v41
	v_lshlrev_b32_e32 v28, 16, v34
	v_and_b32_e32 v29, 0xffff0000, v34
	v_lshlrev_b32_e32 v30, 16, v35
	v_and_b32_e32 v31, 0xffff0000, v35
	v_lshlrev_b32_e32 v32, 16, v36
	v_and_b32_e32 v33, 0xffff0000, v36
	v_lshlrev_b32_e32 v34, 16, v37
	v_and_b32_e32 v35, 0xffff0000, v37
	s_nop 0
	v_pk_add_f32 v[8:9], v[8:9], v[214:215]
	v_pk_add_f32 v[6:7], v[6:7], v[212:213]
	v_pk_add_f32 v[4:5], v[4:5], v[218:219]
	v_pk_add_f32 v[2:3], v[2:3], v[216:217]
	v_mul_f32_e32 v6, 0xbfb8aa3b, v6
	v_mul_f32_e32 v7, 0xbfb8aa3b, v7
	v_mul_f32_e32 v8, 0xbfb8aa3b, v8
	v_mul_f32_e32 v9, 0xbfb8aa3b, v9
	v_mul_f32_e32 v2, 0xbfb8aa3b, v2
	v_mul_f32_e32 v3, 0xbfb8aa3b, v3
	v_mul_f32_e32 v4, 0xbfb8aa3b, v4
	v_mul_f32_e32 v5, 0xbfb8aa3b, v5
	v_exp_f32_e32 v6, v6
	v_exp_f32_e32 v7, v7
	v_exp_f32_e32 v8, v8
	v_exp_f32_e32 v9, v9
	v_exp_f32_e32 v2, v2
	v_exp_f32_e32 v3, v3
	v_exp_f32_e32 v4, v4
	v_exp_f32_e32 v5, v5
	v_add_f32_e32 v6, 1.0, v6
	v_add_f32_e32 v7, 1.0, v7
	v_add_f32_e32 v8, 1.0, v8
	v_add_f32_e32 v9, 1.0, v9
	v_add_f32_e32 v10, 1.0, v2
	v_add_f32_e32 v11, 1.0, v3
	v_add_f32_e32 v12, 1.0, v4
	v_add_f32_e32 v13, 1.0, v5
	v_rcp_f32_e32 v2, v6
	v_rcp_f32_e32 v3, v7
	v_rcp_f32_e32 v4, v8
	v_rcp_f32_e32 v5, v9
	v_rcp_f32_e32 v6, v10
	v_rcp_f32_e32 v8, v12
	v_rcp_f32_e32 v9, v13
	v_rcp_f32_e32 v7, v11
	v_pk_mul_f32 v[4:5], v[4:5], v[20:21]
	v_pk_mul_f32 v[2:3], v[2:3], v[18:19]
	v_pk_mul_f32 v[8:9], v[8:9], v[24:25]
	v_pk_mul_f32 v[6:7], v[6:7], v[22:23]
	v_pk_mul_f32 v[4:5], v[4:5], v[30:31]
	v_pk_mul_f32 v[2:3], v[2:3], v[28:29]
	v_pk_mul_f32 v[8:9], v[8:9], v[34:35]
	v_pk_mul_f32 v[6:7], v[6:7], v[32:33]
	v_cvt_pk_bf16_f32 v2, v2, v3
	v_cvt_pk_bf16_f32 v3, v4, v5
	s_nop 0
	v_cvt_pk_bf16_f32 v4, v6, v7
	v_cvt_pk_bf16_f32 v5, v8, v9
	global_store_dwordx4 v[26:27], v[2:5], off offset:256
	s_waitcnt vmcnt(0)
	s_barrier

.LBB0_1309:
	s_waitcnt vmcnt(4)
	v_readlane_b32 s50, v240, 29
	v_readlane_b32 s51, v240, 30
	v_mov_b64_e32 v[2:3], v[34:35]
	s_add_i32 s89, s89, s50
	v_mov_b64_e32 v[4:5], v[36:37]
	v_mov_b64_e32 v[6:7], v[38:39]
	v_mov_b64_e32 v[8:9], v[40:41]
	v_mov_b64_e32 v[10:11], v[42:43]
	v_mov_b64_e32 v[12:13], v[44:45]
	v_mov_b64_e32 v[14:15], v[46:47]
	v_mov_b64_e32 v[16:17], v[48:49]
	v_mov_b64_e32 v[18:19], v[50:51]
	v_mov_b64_e32 v[20:21], v[52:53]
	v_mov_b64_e32 v[22:23], v[54:55]
	v_mov_b64_e32 v[24:25], v[56:57]
	v_mov_b64_e32 v[26:27], v[58:59]
	v_mov_b64_e32 v[28:29], v[60:61]
	v_mov_b64_e32 v[30:31], v[62:63]
	v_mov_b64_e32 v[32:33], v[64:65]
	v_mov_b32_e32 v65, v68
	v_mov_b32_e32 v64, v111
	v_mov_b32_e32 v63, v110
	v_mov_b32_e32 v62, v109
	v_mov_b32_e32 v61, v108
	v_mov_b32_e32 v60, v107
	v_mov_b32_e32 v59, v106
	v_mov_b32_e32 v58, v105
	v_mov_b32_e32 v57, v104
	v_mov_b32_e32 v56, v103
	v_mov_b32_e32 v55, v102
	v_mov_b32_e32 v54, v97
	v_mov_b32_e32 v53, v96
	v_mov_b32_e32 v52, v95
	v_mov_b32_e32 v51, v94
	v_mov_b32_e32 v50, v93
	v_mov_b32_e32 v49, v92
	v_mov_b32_e32 v48, v91
	v_mov_b32_e32 v47, v90
	v_mov_b32_e32 v46, v89
	v_mov_b32_e32 v45, v88
	v_mov_b32_e32 v44, v87
	v_mov_b32_e32 v43, v86
	v_mov_b32_e32 v42, v85
	v_mov_b32_e32 v41, v84
	v_mov_b32_e32 v40, v83
	v_mov_b32_e32 v39, v82
	v_mov_b32_e32 v38, v81
	v_mov_b32_e32 v37, v80
	v_mov_b32_e32 v36, v79
	v_mov_b32_e32 v35, v78
	v_mov_b32_e32 v34, v77
	s_mov_b32 s71, s83
	s_mov_b32 s70, s82
	s_mov_b32 s54, s88
	s_mov_b64 s[50:51], s[18:19]
	s_mov_b32 s83, s20
	s_mov_b32 s82, s90
	s_mov_b32 s88, s21
	s_mov_b64 s[18:19], s[60:61]

.LBB0_1339:
	v_cvt_f32_u32_e32 v67, s95
	s_add_u32 s55, s66, s68
	s_addc_u32 s66, s67, s69
	s_sub_i32 s67, 0, s95
	v_rcp_iflag_f32_e32 v67, v67
	s_abs_i32 s21, s94
	s_ashr_i32 s20, s94, 31
	v_mul_f32_e32 v67, 0x4f7ffffe, v67
	v_cvt_u32_f32_e32 v67, v67
	s_nop 0
	v_readfirstlane_b32 s68, v67
	s_mul_i32 s67, s67, s68
	s_mul_hi_u32 s67, s68, s67
	s_add_i32 s68, s68, s67
	s_mul_hi_u32 s67, s21, s68
	s_mul_i32 s68, s67, s95
	s_sub_i32 s21, s21, s68
	s_add_i32 s68, s67, 1
	s_sub_i32 s69, s21, s95
	s_cmp_ge_u32 s21, s95
	s_cselect_b32 s67, s68, s67
	s_cselect_b32 s21, s69, s21
	s_add_i32 s68, s67, 1
	s_cmp_ge_u32 s21, s95
	s_cselect_b32 s21, s68, s67
	s_xor_b32 s21, s21, s20
	s_sub_i32 s67, s21, s20
	s_mul_i32 s20, s67, s95
	s_sub_i32 s68, s94, s20
	s_cmpk_gt_i32 s68, 0x7f
	s_cselect_b64 s[20:21], -1, 0
	s_and_b64 s[20:21], s[64:65], s[20:21]
	s_and_b64 s[20:21], s[20:21], exec
	s_cselect_b32 s21, 16, 0
	s_lshl_b32 s20, s68, 5
	s_or_b32 s64, s21, s20
	s_ashr_i32 s65, s64, 31
	s_lshl_b32 s21, s67, 6
	s_lshl_b64 s[64:65], s[64:65], 2
	s_add_u32 s64, s55, s64
	v_or_b32_e32 v67, s21, v70
	s_addc_u32 s65, s66, s65
	s_ashr_i32 s55, s21, 31
	v_lshl_add_u64 v[68:69], s[64:65], 0, v[172:173]
	s_mul_i32 s55, s62, s55
	v_mul_lo_u32 v77, s63, v67
	v_mad_u64_u32 v[78:79], s[64:65], s62, v67, 0
	v_add3_u32 v79, v79, s55, v77
	v_lshl_add_u64 v[78:79], v[78:79], 2, v[68:69]
	global_load_dword v77, v[78:79], off
	v_or_b32_e32 v78, 2, v67
	v_mul_lo_u32 v80, s63, v78
	v_mad_u64_u32 v[78:79], s[64:65], s62, v78, 0
	v_add3_u32 v79, v79, s55, v80
	v_lshl_add_u64 v[78:79], v[78:79], 2, v[68:69]
	global_load_dword v78, v[78:79], off
	v_or_b32_e32 v79, 4, v67
	v_mul_lo_u32 v82, s63, v79
	v_mad_u64_u32 v[80:81], s[64:65], s62, v79, 0
	v_add3_u32 v81, v81, s55, v82
	v_lshl_add_u64 v[80:81], v[80:81], 2, v[68:69]
	global_load_dword v79, v[80:81], off
	v_or_b32_e32 v80, 6, v67
	v_mul_lo_u32 v82, s63, v80
	v_mad_u64_u32 v[80:81], s[64:65], s62, v80, 0
	v_add3_u32 v81, v81, s55, v82
	v_lshl_add_u64 v[80:81], v[80:81], 2, v[68:69]
	global_load_dword v80, v[80:81], off
	v_or_b32_e32 v81, 8, v67
	v_mul_lo_u32 v84, s63, v81
	v_mad_u64_u32 v[82:83], s[64:65], s62, v81, 0
	v_add3_u32 v83, v83, s55, v84
	v_lshl_add_u64 v[82:83], v[82:83], 2, v[68:69]
	global_load_dword v81, v[82:83], off
	v_or_b32_e32 v82, 10, v67
	v_mul_lo_u32 v84, s63, v82
	v_mad_u64_u32 v[82:83], s[64:65], s62, v82, 0
	v_add3_u32 v83, v83, s55, v84
	v_lshl_add_u64 v[82:83], v[82:83], 2, v[68:69]
	global_load_dword v82, v[82:83], off
	v_or_b32_e32 v83, 12, v67
	v_mul_lo_u32 v86, s63, v83
	v_mad_u64_u32 v[84:85], s[64:65], s62, v83, 0
	v_add3_u32 v85, v85, s55, v86
	v_lshl_add_u64 v[84:85], v[84:85], 2, v[68:69]
	global_load_dword v83, v[84:85], off
	v_or_b32_e32 v84, 14, v67
	v_mul_lo_u32 v86, s63, v84
	v_mad_u64_u32 v[84:85], s[64:65], s62, v84, 0
	v_add3_u32 v85, v85, s55, v86
	v_lshl_add_u64 v[84:85], v[84:85], 2, v[68:69]
	global_load_dword v84, v[84:85], off
	v_or_b32_e32 v85, 16, v67
	v_mul_lo_u32 v88, s63, v85
	v_mad_u64_u32 v[86:87], s[64:65], s62, v85, 0
	v_add3_u32 v87, v87, s55, v88
	v_lshl_add_u64 v[86:87], v[86:87], 2, v[68:69]
	global_load_dword v85, v[86:87], off
	v_or_b32_e32 v86, 18, v67
	v_mul_lo_u32 v88, s63, v86
	v_mad_u64_u32 v[86:87], s[64:65], s62, v86, 0
	v_add3_u32 v87, v87, s55, v88
	v_lshl_add_u64 v[86:87], v[86:87], 2, v[68:69]
	global_load_dword v86, v[86:87], off
	v_or_b32_e32 v87, 20, v67
	v_mul_lo_u32 v90, s63, v87
	v_mad_u64_u32 v[88:89], s[64:65], s62, v87, 0
	v_add3_u32 v89, v89, s55, v90
	v_lshl_add_u64 v[88:89], v[88:89], 2, v[68:69]
	global_load_dword v87, v[88:89], off
	v_or_b32_e32 v88, 22, v67
	v_mul_lo_u32 v90, s63, v88
	v_mad_u64_u32 v[88:89], s[64:65], s62, v88, 0
	v_add3_u32 v89, v89, s55, v90
	v_lshl_add_u64 v[88:89], v[88:89], 2, v[68:69]
	global_load_dword v88, v[88:89], off
	v_or_b32_e32 v89, 24, v67
	v_mul_lo_u32 v92, s63, v89
	v_mad_u64_u32 v[90:91], s[64:65], s62, v89, 0
	v_add3_u32 v91, v91, s55, v92
	v_lshl_add_u64 v[90:91], v[90:91], 2, v[68:69]
	global_load_dword v89, v[90:91], off
	v_or_b32_e32 v90, 26, v67
	v_mul_lo_u32 v92, s63, v90
	v_mad_u64_u32 v[90:91], s[64:65], s62, v90, 0
	v_add3_u32 v91, v91, s55, v92
	v_lshl_add_u64 v[90:91], v[90:91], 2, v[68:69]
	global_load_dword v90, v[90:91], off
	v_or_b32_e32 v91, 28, v67
	v_mul_lo_u32 v94, s63, v91
	v_mad_u64_u32 v[92:93], s[64:65], s62, v91, 0
	v_add3_u32 v93, v93, s55, v94
	v_lshl_add_u64 v[92:93], v[92:93], 2, v[68:69]
	global_load_dword v91, v[92:93], off
	v_or_b32_e32 v92, 30, v67
	v_mul_lo_u32 v94, s63, v92
	v_mad_u64_u32 v[92:93], s[64:65], s62, v92, 0
	v_add3_u32 v93, v93, s55, v94
	v_lshl_add_u64 v[92:93], v[92:93], 2, v[68:69]
	global_load_dword v92, v[92:93], off
	v_or_b32_e32 v93, 32, v67
	v_mul_lo_u32 v96, s63, v93
	v_mad_u64_u32 v[94:95], s[64:65], s62, v93, 0
	v_add3_u32 v95, v95, s55, v96
	v_lshl_add_u64 v[94:95], v[94:95], 2, v[68:69]
	global_load_dword v93, v[94:95], off
	v_or_b32_e32 v94, 34, v67
	v_mul_lo_u32 v96, s63, v94
	v_mad_u64_u32 v[94:95], s[64:65], s62, v94, 0
	v_add3_u32 v95, v95, s55, v96
	v_lshl_add_u64 v[94:95], v[94:95], 2, v[68:69]
	global_load_dword v94, v[94:95], off
	v_or_b32_e32 v95, 36, v67
	v_mul_lo_u32 v102, s63, v95
	v_mad_u64_u32 v[96:97], s[64:65], s62, v95, 0
	v_add3_u32 v97, v97, s55, v102
	v_lshl_add_u64 v[96:97], v[96:97], 2, v[68:69]
	global_load_dword v95, v[96:97], off
	v_or_b32_e32 v96, 38, v67
	v_mul_lo_u32 v102, s63, v96
	v_mad_u64_u32 v[96:97], s[64:65], s62, v96, 0
	v_add3_u32 v97, v97, s55, v102
	v_lshl_add_u64 v[96:97], v[96:97], 2, v[68:69]
	global_load_dword v96, v[96:97], off
	v_or_b32_e32 v97, 40, v67
	v_mul_lo_u32 v104, s63, v97
	v_mad_u64_u32 v[102:103], s[64:65], s62, v97, 0
	v_add3_u32 v103, v103, s55, v104
	v_lshl_add_u64 v[102:103], v[102:103], 2, v[68:69]
	global_load_dword v97, v[102:103], off
	v_or_b32_e32 v102, 42, v67
	v_mul_lo_u32 v104, s63, v102
	v_mad_u64_u32 v[102:103], s[64:65], s62, v102, 0
	v_add3_u32 v103, v103, s55, v104
	v_lshl_add_u64 v[102:103], v[102:103], 2, v[68:69]
	global_load_dword v102, v[102:103], off
	v_or_b32_e32 v103, 44, v67
	v_mul_lo_u32 v106, s63, v103
	v_mad_u64_u32 v[104:105], s[64:65], s62, v103, 0
	v_add3_u32 v105, v105, s55, v106
	v_lshl_add_u64 v[104:105], v[104:105], 2, v[68:69]
	global_load_dword v103, v[104:105], off
	v_or_b32_e32 v104, 46, v67
	v_mul_lo_u32 v106, s63, v104
	v_mad_u64_u32 v[104:105], s[64:65], s62, v104, 0
	v_add3_u32 v105, v105, s55, v106
	v_lshl_add_u64 v[104:105], v[104:105], 2, v[68:69]
	global_load_dword v104, v[104:105], off
	v_or_b32_e32 v105, 48, v67
	v_mul_lo_u32 v108, s63, v105
	v_mad_u64_u32 v[106:107], s[64:65], s62, v105, 0
	v_add3_u32 v107, v107, s55, v108
	v_lshl_add_u64 v[106:107], v[106:107], 2, v[68:69]
	global_load_dword v105, v[106:107], off
	v_or_b32_e32 v106, 50, v67
	v_mul_lo_u32 v108, s63, v106
	v_mad_u64_u32 v[106:107], s[64:65], s62, v106, 0
	v_add3_u32 v107, v107, s55, v108
	v_lshl_add_u64 v[106:107], v[106:107], 2, v[68:69]
	global_load_dword v106, v[106:107], off
	v_or_b32_e32 v107, 52, v67
	v_mul_lo_u32 v110, s63, v107
	v_mad_u64_u32 v[108:109], s[64:65], s62, v107, 0
	v_add3_u32 v109, v109, s55, v110
	v_lshl_add_u64 v[108:109], v[108:109], 2, v[68:69]
	global_load_dword v107, v[108:109], off
	v_or_b32_e32 v108, 54, v67
	v_mul_lo_u32 v110, s63, v108
	v_mad_u64_u32 v[108:109], s[64:65], s62, v108, 0
	v_add3_u32 v109, v109, s55, v110
	v_lshl_add_u64 v[108:109], v[108:109], 2, v[68:69]
	global_load_dword v108, v[108:109], off
	v_or_b32_e32 v109, 56, v67
	v_mul_lo_u32 v112, s63, v109
	v_mad_u64_u32 v[110:111], s[64:65], s62, v109, 0
	v_add3_u32 v111, v111, s55, v112
	v_lshl_add_u64 v[110:111], v[110:111], 2, v[68:69]
	global_load_dword v109, v[110:111], off
	v_or_b32_e32 v110, 58, v67
	v_mul_lo_u32 v112, s63, v110
	v_mad_u64_u32 v[110:111], s[64:65], s62, v110, 0
	v_add3_u32 v111, v111, s55, v112
	v_lshl_add_u64 v[110:111], v[110:111], 2, v[68:69]
	global_load_dword v110, v[110:111], off
	v_or_b32_e32 v111, 60, v67
	v_mul_lo_u32 v114, s63, v111
	v_mad_u64_u32 v[112:113], s[64:65], s62, v111, 0
	v_add3_u32 v113, v113, s55, v114
	v_lshl_add_u64 v[112:113], v[112:113], 2, v[68:69]
	v_or_b32_e32 v67, 62, v67
	global_load_dword v111, v[112:113], off
	v_mul_lo_u32 v114, s63, v67
	v_mad_u64_u32 v[112:113], s[62:63], s62, v67, 0
	v_add3_u32 v113, v113, s55, v114
	v_lshl_add_u64 v[68:69], v[112:113], 2, v[68:69]
	global_load_dword v68, v[68:69], off
	v_readlane_b32 s94, v238, 0
	v_readlane_b32 s95, v238, 1
	v_readlane_b32 s68, v238, 7
	v_readlane_b32 s95, v238, 2
	v_readlane_b32 s69, v238, 8
	s_waitcnt vmcnt(32) lgkmcnt(0)
	s_branch .Lcvt_go_p8

.Lcvt_go_p8:
	v_add_u32_e32 v67, 0x400, v76
	ds_write2_b32 v76, v2, v3 offset1:66
	ds_write2_b32 v76, v4, v5 offset0:132 offset1:198
	ds_write2_b32 v67, v6, v7 offset0:8 offset1:74
	ds_write2_b32 v67, v8, v9 offset0:140 offset1:206
	v_add_u32_e32 v67, 0x800, v76
	ds_write2_b32 v67, v10, v11 offset0:16 offset1:82
	ds_write2_b32 v67, v12, v13 offset0:148 offset1:214
	v_add_u32_e32 v67, 0xc00, v76
	ds_write2_b32 v67, v14, v15 offset0:24 offset1:90
	ds_write2_b32 v67, v16, v17 offset0:156 offset1:222
	v_add_u32_e32 v67, 0x1000, v76
	ds_write2_b32 v67, v18, v19 offset0:32 offset1:98
	ds_write2_b32 v67, v20, v21 offset0:164 offset1:230
	v_add_u32_e32 v67, 0x1400, v76
	ds_write2_b32 v67, v22, v23 offset0:40 offset1:106
	ds_write2_b32 v67, v24, v25 offset0:172 offset1:238
	v_add_u32_e32 v67, 0x1800, v76
	ds_write2_b32 v67, v26, v27 offset0:48 offset1:114
	ds_write2_b32 v67, v28, v29 offset0:180 offset1:246
	v_add_u32_e32 v67, 0x1c00, v76
	ds_write2_b32 v67, v30, v31 offset0:56 offset1:122
	ds_write2_b32 v67, v32, v33 offset0:188 offset1:254
	s_waitcnt lgkmcnt(0)
	ds_read2_b32 v[116:117], v72 offset1:8
	ds_read2_b32 v[118:119], v72 offset0:33 offset1:41
	ds_read2_b32 v[120:121], v72 offset0:66 offset1:74
	ds_read2_b32 v[122:123], v72 offset0:99 offset1:107
	ds_read2_b32 v[124:125], v72 offset0:132 offset1:140
	s_waitcnt lgkmcnt(4)
	v_bfe_u32 v67, v116, 16, 1
	v_add3_u32 v67, v116, v67, s12
	s_waitcnt lgkmcnt(3)
	v_bfe_u32 v69, v118, 16, 1
	v_lshrrev_b32_e32 v67, 16, v67
	v_add3_u32 v69, v118, v69, s12
	s_mov_b32 vcc_lo, 0xffff0000
	ds_read2_b32 v[126:127], v72 offset0:165 offset1:173
	v_and_or_b32 v112, v69, vcc_lo, v67
	s_waitcnt lgkmcnt(3)
	v_bfe_u32 v67, v120, 16, 1
	v_add3_u32 v67, v120, v67, s12
	s_waitcnt lgkmcnt(2)
	v_bfe_u32 v69, v122, 16, 1
	ds_read2_b32 v[128:129], v72 offset0:198 offset1:206
	v_lshrrev_b32_e32 v67, 16, v67
	v_add3_u32 v69, v122, v69, s12
	ds_read2_b32 v[130:131], v72 offset0:231 offset1:239
	v_and_or_b32 v113, v69, vcc_lo, v67
	s_waitcnt lgkmcnt(3)
	v_bfe_u32 v67, v124, 16, 1
	v_add3_u32 v67, v124, v67, s12
	s_waitcnt lgkmcnt(2)
	v_bfe_u32 v69, v126, 16, 1
	v_lshrrev_b32_e32 v67, 16, v67
	v_add3_u32 v69, v126, v69, s12
	v_and_or_b32 v114, v69, vcc_lo, v67
	s_waitcnt lgkmcnt(1)
	v_bfe_u32 v67, v128, 16, 1
	v_add3_u32 v67, v128, v67, s12
	s_waitcnt lgkmcnt(0)
	v_bfe_u32 v69, v130, 16, 1
	v_lshrrev_b32_e32 v67, 16, v67
	v_add3_u32 v69, v130, v69, s12
	v_and_or_b32 v115, v69, vcc_lo, v67
	v_add_u32_e32 v67, s71, v71
	v_mad_u64_u32 v[132:133], s[64:65], v67, s70, 0
	v_ashrrev_i32_e32 v69, 31, v67
	v_mov_b32_e32 v116, v133
	v_mad_u64_u32 v[134:135], s[64:65], v69, s70, v[116:117]
	v_mov_b32_e32 v133, v134
	s_ashr_i32 s55, s54, 31
	v_lshl_add_u64 v[132:133], v[132:133], 1, s[50:51]
	s_lshl_b64 s[64:65], s[54:55], 1
	v_lshl_add_u64 v[132:133], v[132:133], 0, s[64:65]
	v_mov_b32_e32 v67, v173
	v_lshl_add_u64 v[132:133], v[132:133], 0, v[66:67]
	v_bfe_u32 v69, v117, 16, 1
	global_store_dwordx4 v[132:133], v[112:115], off
	v_add3_u32 v69, v117, v69, s12
	v_lshrrev_b32_e32 v69, 16, v69
	v_bfe_u32 v112, v119, 16, 1
	v_add3_u32 v112, v119, v112, s12
	v_and_or_b32 v112, v112, vcc_lo, v69
	v_bfe_u32 v69, v121, 16, 1
	v_add3_u32 v69, v121, v69, s12
	v_bfe_u32 v113, v123, 16, 1
	v_lshrrev_b32_e32 v69, 16, v69
	v_add3_u32 v113, v123, v113, s12
	v_and_or_b32 v113, v113, vcc_lo, v69
	v_bfe_u32 v69, v125, 16, 1
	v_add3_u32 v69, v125, v69, s12
	v_bfe_u32 v114, v127, 16, 1
	v_lshrrev_b32_e32 v69, 16, v69
	v_add3_u32 v114, v127, v114, s12
	v_and_or_b32 v114, v114, vcc_lo, v69
	v_bfe_u32 v69, v129, 16, 1
	v_add3_u32 v69, v129, v69, s12
	v_bfe_u32 v115, v131, 16, 1
	v_lshrrev_b32_e32 v69, 16, v69
	v_add3_u32 v115, v131, v115, s12
	v_and_or_b32 v115, v115, vcc_lo, v69
	v_add_u32_e32 v69, s71, v73
	v_mad_u64_u32 v[116:117], s[66:67], v69, s70, 0
	v_ashrrev_i32_e32 v119, 31, v69
	v_mov_b32_e32 v118, v117
	v_mad_u64_u32 v[118:119], s[66:67], v119, s70, v[118:119]
	v_mov_b32_e32 v117, v118
	v_lshl_add_u64 v[116:117], v[116:117], 1, s[50:51]
	v_lshl_add_u64 v[116:117], v[116:117], 0, s[64:65]
	ds_read2_b32 v[118:119], v72 offset0:16 offset1:24
	v_lshl_add_u64 v[116:117], v[116:117], 0, v[66:67]
	global_store_dwordx4 v[116:117], v[112:115], off
	ds_read2_b32 v[116:117], v72 offset0:49 offset1:57
	ds_read2_b32 v[120:121], v72 offset0:82 offset1:90
	ds_read2_b32 v[122:123], v72 offset0:115 offset1:123
	s_waitcnt lgkmcnt(3)
	v_bfe_u32 v69, v118, 16, 1
	v_add3_u32 v69, v118, v69, s12
	s_waitcnt lgkmcnt(2)
	v_bfe_u32 v112, v116, 16, 1
	ds_read2_b32 v[124:125], v72 offset0:148 offset1:156
	v_lshrrev_b32_e32 v69, 16, v69
	v_add3_u32 v112, v116, v112, s12
	ds_read2_b32 v[126:127], v72 offset0:181 offset1:189
	v_and_or_b32 v112, v112, vcc_lo, v69
	s_waitcnt lgkmcnt(3)
	v_bfe_u32 v69, v120, 16, 1
	v_add3_u32 v69, v120, v69, s12
	s_waitcnt lgkmcnt(2)
	v_bfe_u32 v113, v122, 16, 1
	ds_read2_b32 v[128:129], v72 offset0:214 offset1:222
	v_lshrrev_b32_e32 v69, 16, v69
	v_add3_u32 v113, v122, v113, s12
	ds_read2_b32 v[130:131], v72 offset0:247 offset1:255
	v_and_or_b32 v113, v113, vcc_lo, v69
	s_waitcnt lgkmcnt(3)
	v_bfe_u32 v69, v124, 16, 1
	v_add3_u32 v69, v124, v69, s12
	s_waitcnt lgkmcnt(2)
	v_bfe_u32 v114, v126, 16, 1
	v_lshrrev_b32_e32 v69, 16, v69
	v_add3_u32 v114, v126, v114, s12
	v_and_or_b32 v114, v114, vcc_lo, v69
	s_waitcnt lgkmcnt(1)
	v_bfe_u32 v69, v128, 16, 1
	v_add3_u32 v69, v128, v69, s12
	s_waitcnt lgkmcnt(0)
	v_bfe_u32 v115, v130, 16, 1
	v_lshrrev_b32_e32 v69, 16, v69
	v_add3_u32 v115, v130, v115, s12
	v_and_or_b32 v115, v115, vcc_lo, v69
	v_add_u32_e32 v69, s71, v74
	v_mad_u64_u32 v[132:133], s[66:67], v69, s70, 0
	v_ashrrev_i32_e32 v118, 31, v69
	v_mov_b32_e32 v116, v133
	v_mad_u64_u32 v[134:135], s[66:67], v118, s70, v[116:117]
	v_mov_b32_e32 v133, v134
	v_lshl_add_u64 v[132:133], v[132:133], 1, s[50:51]
	v_lshl_add_u64 v[132:133], v[132:133], 0, s[64:65]
	v_lshl_add_u64 v[132:133], v[132:133], 0, v[66:67]
	v_bfe_u32 v69, v119, 16, 1
	global_store_dwordx4 v[132:133], v[112:115], off
	v_add3_u32 v69, v119, v69, s12
	v_lshrrev_b32_e32 v69, 16, v69
	v_bfe_u32 v112, v117, 16, 1
	v_add3_u32 v112, v117, v112, s12
	v_and_or_b32 v112, v112, vcc_lo, v69
	v_bfe_u32 v69, v121, 16, 1
	v_add3_u32 v69, v121, v69, s12
	v_bfe_u32 v113, v123, 16, 1
	v_lshrrev_b32_e32 v69, 16, v69
	v_add3_u32 v113, v123, v113, s12
	v_and_or_b32 v113, v113, vcc_lo, v69
	v_bfe_u32 v69, v125, 16, 1
	v_add3_u32 v69, v125, v69, s12
	v_bfe_u32 v114, v127, 16, 1
	v_lshrrev_b32_e32 v69, 16, v69
	v_add3_u32 v114, v127, v114, s12
	v_and_or_b32 v114, v114, vcc_lo, v69
	v_bfe_u32 v69, v129, 16, 1
	v_add3_u32 v69, v129, v69, s12
	v_bfe_u32 v115, v131, 16, 1
	v_lshrrev_b32_e32 v69, 16, v69
	v_add3_u32 v115, v131, v115, s12
	v_and_or_b32 v115, v115, vcc_lo, v69
	v_add_u32_e32 v69, s71, v75
	v_mad_u64_u32 v[116:117], s[66:67], v69, s70, 0
	v_ashrrev_i32_e32 v119, 31, v69
	v_mov_b32_e32 v118, v117
	v_mad_u64_u32 v[118:119], s[66:67], v119, s70, v[118:119]
	v_mov_b32_e32 v117, v118
	v_lshl_add_u64 v[116:117], v[116:117], 1, s[50:51]
	v_lshl_add_u64 v[116:117], v[116:117], 0, s[64:65]
	v_lshl_add_u64 v[116:117], v[116:117], 0, v[66:67]
	global_store_dwordx4 v[116:117], v[112:115], off
	s_waitcnt lgkmcnt(0)
	s_xor_b64 s[62:63], s[58:59], -1
	s_andn2_b64 vcc, exec, s[58:59]
	s_cbranch_vccz .LBB0_1309
	s_mov_b64 s[56:57], 0
	s_branch .LBB0_1310
